# rotated BN=256 GEMM loops: DMA pieces behind MFMAs 8,11,13,14 of the first half-step
# baseline (speedup 1.0000x reference)
.Lgf_G4x_top:
	s_waitcnt vmcnt(4)
	s_waitcnt lgkmcnt(0)
	s_barrier
	v_mfma_f32_16x16x32_bf16 v[158:161], v[122:125], v[150:153], v[158:161]
	v_mfma_f32_16x16x32_bf16 v[94:97], v[126:129], v[150:153], v[94:97]
	s_add_i32 s28, s31, 0xfffe8000
	s_and_b32 s34, s28, 0x10000
	v_add_u32_e32 v170, s34, v230
	ds_read_b128 v[162:165], v170
	v_mfma_f32_16x16x32_bf16 v[62:65], v[130:133], v[150:153], v[62:65]
	ds_read_b128 v[166:169], v170 offset:1024
	v_mfma_f32_16x16x32_bf16 v[30:33], v[134:137], v[150:153], v[30:33]
	ds_read_b128 v[232:235], v170 offset:2048
	v_mfma_f32_16x16x32_bf16 v[118:121], v[122:125], v[146:149], v[118:121]
	ds_read_b128 v[236:239], v170 offset:3072
	s_and_b32 s89, s31, 0x18000
	s_add_i32 s89, s89, s88
	s_mov_b32 m0, s89
	v_mfma_f32_16x16x32_bf16 v[86:89], v[126:129], v[146:149], v[86:89]
	v_mfma_f32_16x16x32_bf16 v[54:57], v[130:133], v[146:149], v[54:57]
	v_mfma_f32_16x16x32_bf16 v[22:25], v[134:137], v[146:149], v[22:25]
	global_load_lds_dwordx4 v186, s[90:91]
	s_add_i32 m0, s89, 0x2000
	v_mfma_f32_16x16x32_bf16 v[110:113], v[122:125], v[142:145], v[110:113]
	v_mfma_f32_16x16x32_bf16 v[78:81], v[126:129], v[142:145], v[78:81]
	v_mfma_f32_16x16x32_bf16 v[46:49], v[130:133], v[142:145], v[46:49]
	global_load_lds_dwordx4 v188, s[90:91]
	s_add_i32 m0, s89, 0x4000
	v_mfma_f32_16x16x32_bf16 v[14:17], v[134:137], v[142:145], v[14:17]
	v_mfma_f32_16x16x32_bf16 v[102:105], v[122:125], v[138:141], v[102:105]
	global_load_lds_dwordx4 v190, s[92:93]
	s_add_i32 m0, s89, 0x6000
	v_mfma_f32_16x16x32_bf16 v[70:73], v[126:129], v[138:141], v[70:73]
	global_load_lds_dwordx4 v192, s[92:93]
	s_add_u32 s90, s90, 64
	s_addc_u32 s91, s91, 0
	s_add_u32 s92, s92, 64
	s_addc_u32 s93, s93, 0
	v_mfma_f32_16x16x32_bf16 v[38:41], v[130:133], v[138:141], v[38:41]
	v_mfma_f32_16x16x32_bf16 v[6:9], v[134:137], v[138:141], v[6:9]
	s_waitcnt lgkmcnt(0)
	v_mfma_f32_16x16x32_bf16 v[154:157], v[122:125], v[162:165], v[154:157]
	s_add_i32 s28, s31, 0xffff0000
	s_and_b32 s35, s28, 0x18000
	v_add_u32_e32 v187, s35, v200
	v_add_u32_e32 v226, s35, v201
	ds_read_b128 v[150:153], v226
	v_mfma_f32_16x16x32_bf16 v[90:93], v[126:129], v[162:165], v[90:93]
	ds_read_b128 v[146:149], v226 offset:1024
	v_mfma_f32_16x16x32_bf16 v[58:61], v[130:133], v[162:165], v[58:61]
	ds_read_b128 v[142:145], v226 offset:2048
	v_mfma_f32_16x16x32_bf16 v[26:29], v[134:137], v[162:165], v[26:29]
	ds_read_b128 v[138:141], v226 offset:3072
	v_mfma_f32_16x16x32_bf16 v[114:117], v[122:125], v[166:169], v[114:117]
	ds_read_b128 v[174:177], v187
	v_mfma_f32_16x16x32_bf16 v[82:85], v[126:129], v[166:169], v[82:85]
	ds_read_b128 v[170:173], v187 offset:1024
	v_mfma_f32_16x16x32_bf16 v[50:53], v[130:133], v[166:169], v[50:53]
	ds_read_b128 v[162:165], v187 offset:3072
	v_mfma_f32_16x16x32_bf16 v[18:21], v[134:137], v[166:169], v[18:21]
	ds_read_b128 v[166:169], v187 offset:2048
	v_mfma_f32_16x16x32_bf16 v[106:109], v[122:125], v[232:235], v[106:109]
	v_mfma_f32_16x16x32_bf16 v[74:77], v[126:129], v[232:235], v[74:77]
	v_mfma_f32_16x16x32_bf16 v[42:45], v[130:133], v[232:235], v[42:45]
	v_mfma_f32_16x16x32_bf16 v[10:13], v[134:137], v[232:235], v[10:13]
	v_mfma_f32_16x16x32_bf16 v[98:101], v[122:125], v[236:239], v[98:101]
	v_mfma_f32_16x16x32_bf16 v[66:69], v[126:129], v[236:239], v[66:69]
	v_mfma_f32_16x16x32_bf16 v[34:37], v[130:133], v[236:239], v[34:37]
	v_mfma_f32_16x16x32_bf16 v[2:5], v[134:137], v[236:239], v[2:5]
	s_waitcnt vmcnt(4)
	s_waitcnt lgkmcnt(0)
	s_barrier
	v_mfma_f32_16x16x32_bf16 v[158:161], v[174:177], v[150:153], v[158:161]
	v_mfma_f32_16x16x32_bf16 v[94:97], v[170:173], v[150:153], v[94:97]
	v_add_u32_e32 v226, s35, v230
	ds_read_b128 v[232:235], v226
	v_mfma_f32_16x16x32_bf16 v[62:65], v[166:169], v[150:153], v[62:65]
	ds_read_b128 v[236:239], v226 offset:1024
	v_mfma_f32_16x16x32_bf16 v[30:33], v[162:165], v[150:153], v[30:33]
	ds_read_b128 v[182:185], v226 offset:2048
	v_mfma_f32_16x16x32_bf16 v[118:121], v[174:177], v[146:149], v[118:121]
	ds_read_b128 v[178:181], v226 offset:3072
	s_add_i32 s89, s34, s88
	s_mov_b32 m0, s89
	v_mfma_f32_16x16x32_bf16 v[86:89], v[170:173], v[146:149], v[86:89]
	v_mfma_f32_16x16x32_bf16 v[54:57], v[166:169], v[146:149], v[54:57]
	v_mfma_f32_16x16x32_bf16 v[22:25], v[162:165], v[146:149], v[22:25]
	global_load_lds_dwordx4 v186, s[90:91]
	s_add_i32 m0, s89, 0x2000
	v_mfma_f32_16x16x32_bf16 v[110:113], v[174:177], v[142:145], v[110:113]
	v_mfma_f32_16x16x32_bf16 v[78:81], v[170:173], v[142:145], v[78:81]
	v_mfma_f32_16x16x32_bf16 v[46:49], v[166:169], v[142:145], v[46:49]
	global_load_lds_dwordx4 v188, s[90:91]
	s_add_i32 m0, s89, 0x4000
	v_mfma_f32_16x16x32_bf16 v[14:17], v[162:165], v[142:145], v[14:17]
	v_mfma_f32_16x16x32_bf16 v[102:105], v[174:177], v[138:141], v[102:105]
	global_load_lds_dwordx4 v190, s[92:93]
	s_add_i32 m0, s89, 0x6000
	v_mfma_f32_16x16x32_bf16 v[70:73], v[170:173], v[138:141], v[70:73]
	global_load_lds_dwordx4 v192, s[92:93]
	s_add_u32 s90, s90, 64
	s_addc_u32 s91, s91, 0
	s_add_u32 s92, s92, 64
	s_addc_u32 s93, s93, 0
	v_mfma_f32_16x16x32_bf16 v[38:41], v[166:169], v[138:141], v[38:41]
	v_mfma_f32_16x16x32_bf16 v[6:9], v[162:165], v[138:141], v[6:9]
	s_waitcnt lgkmcnt(0)
	v_mfma_f32_16x16x32_bf16 v[154:157], v[174:177], v[232:235], v[154:157]
	s_add_i32 s24, s31, 0xffff8000
	s_and_b32 s24, s24, 0x10000
	v_add_u32_e32 v187, s24, v200
	v_add_u32_e32 v226, s24, v201
	ds_read_b128 v[150:153], v226
	v_mfma_f32_16x16x32_bf16 v[90:93], v[170:173], v[232:235], v[90:93]
	ds_read_b128 v[146:149], v226 offset:1024
	v_mfma_f32_16x16x32_bf16 v[58:61], v[166:169], v[232:235], v[58:61]
	ds_read_b128 v[142:145], v226 offset:2048
	v_mfma_f32_16x16x32_bf16 v[26:29], v[162:165], v[232:235], v[26:29]
	ds_read_b128 v[138:141], v226 offset:3072
	v_mfma_f32_16x16x32_bf16 v[114:117], v[174:177], v[236:239], v[114:117]
	ds_read_b128 v[122:125], v187
	v_mfma_f32_16x16x32_bf16 v[82:85], v[170:173], v[236:239], v[82:85]
	ds_read_b128 v[126:129], v187 offset:1024
	v_mfma_f32_16x16x32_bf16 v[50:53], v[166:169], v[236:239], v[50:53]
	ds_read_b128 v[130:133], v187 offset:2048
	v_mfma_f32_16x16x32_bf16 v[18:21], v[162:165], v[236:239], v[18:21]
	ds_read_b128 v[134:137], v187 offset:3072
	s_add_i32 s19, s19, 2
	s_add_u32 s20, s20, 0x80
	s_addc_u32 s21, s21, 0
	s_add_i32 s31, s31, 0x10000
	v_mfma_f32_16x16x32_bf16 v[106:109], v[174:177], v[182:185], v[106:109]
	v_mfma_f32_16x16x32_bf16 v[74:77], v[170:173], v[182:185], v[74:77]
	v_mfma_f32_16x16x32_bf16 v[42:45], v[166:169], v[182:185], v[42:45]
	v_mfma_f32_16x16x32_bf16 v[10:13], v[162:165], v[182:185], v[10:13]
	v_mfma_f32_16x16x32_bf16 v[98:101], v[174:177], v[178:181], v[98:101]
	v_mfma_f32_16x16x32_bf16 v[66:69], v[170:173], v[178:181], v[66:69]
	v_mfma_f32_16x16x32_bf16 v[34:37], v[166:169], v[178:181], v[34:37]
	v_mfma_f32_16x16x32_bf16 v[2:5], v[162:165], v[178:181], v[2:5]
	s_cmp_lt_u32 s19, 28
	s_cbranch_scc1 .Lgf_G4x_top
	s_waitcnt vmcnt(4)
	s_waitcnt lgkmcnt(0)
	s_barrier
	v_mfma_f32_16x16x32_bf16 v[158:161], v[122:125], v[150:153], v[158:161]
	v_mfma_f32_16x16x32_bf16 v[94:97], v[126:129], v[150:153], v[94:97]
	s_add_i32 s28, s31, 0xfffe8000
	s_and_b32 s34, s28, 0x10000
	v_add_u32_e32 v170, s34, v230
	ds_read_b128 v[162:165], v170
	v_mfma_f32_16x16x32_bf16 v[62:65], v[130:133], v[150:153], v[62:65]
	ds_read_b128 v[166:169], v170 offset:1024
	v_mfma_f32_16x16x32_bf16 v[30:33], v[134:137], v[150:153], v[30:33]
	ds_read_b128 v[232:235], v170 offset:2048
	v_mfma_f32_16x16x32_bf16 v[118:121], v[122:125], v[146:149], v[118:121]
	ds_read_b128 v[236:239], v170 offset:3072
	s_and_b32 s89, s31, 0x18000
	s_add_i32 s89, s89, s88
	s_mov_b32 m0, s89
	v_mfma_f32_16x16x32_bf16 v[86:89], v[126:129], v[146:149], v[86:89]
	v_mfma_f32_16x16x32_bf16 v[54:57], v[130:133], v[146:149], v[54:57]
	v_mfma_f32_16x16x32_bf16 v[22:25], v[134:137], v[146:149], v[22:25]
	global_load_lds_dwordx4 v186, s[90:91]
	s_add_i32 m0, s89, 0x2000
	v_mfma_f32_16x16x32_bf16 v[110:113], v[122:125], v[142:145], v[110:113]
	v_mfma_f32_16x16x32_bf16 v[78:81], v[126:129], v[142:145], v[78:81]
	v_mfma_f32_16x16x32_bf16 v[46:49], v[130:133], v[142:145], v[46:49]
	global_load_lds_dwordx4 v188, s[90:91]
	s_add_i32 m0, s89, 0x4000
	v_mfma_f32_16x16x32_bf16 v[14:17], v[134:137], v[142:145], v[14:17]
	v_mfma_f32_16x16x32_bf16 v[102:105], v[122:125], v[138:141], v[102:105]
	global_load_lds_dwordx4 v190, s[92:93]
	s_add_i32 m0, s89, 0x6000
	v_mfma_f32_16x16x32_bf16 v[70:73], v[126:129], v[138:141], v[70:73]
	global_load_lds_dwordx4 v192, s[92:93]
	s_add_u32 s90, s90, 64
	s_addc_u32 s91, s91, 0
	s_add_u32 s92, s92, 64
	s_addc_u32 s93, s93, 0
	v_mfma_f32_16x16x32_bf16 v[38:41], v[130:133], v[138:141], v[38:41]
	v_mfma_f32_16x16x32_bf16 v[6:9], v[134:137], v[138:141], v[6:9]
	s_waitcnt lgkmcnt(0)
	v_mfma_f32_16x16x32_bf16 v[154:157], v[122:125], v[162:165], v[154:157]
	s_add_i32 s28, s31, 0xffff0000
	s_and_b32 s35, s28, 0x18000
	v_add_u32_e32 v187, s35, v200
	v_add_u32_e32 v226, s35, v201
	ds_read_b128 v[150:153], v226
	v_mfma_f32_16x16x32_bf16 v[90:93], v[126:129], v[162:165], v[90:93]
	ds_read_b128 v[146:149], v226 offset:1024
	v_mfma_f32_16x16x32_bf16 v[58:61], v[130:133], v[162:165], v[58:61]
	ds_read_b128 v[142:145], v226 offset:2048
	v_mfma_f32_16x16x32_bf16 v[26:29], v[134:137], v[162:165], v[26:29]
	ds_read_b128 v[138:141], v226 offset:3072
	v_mfma_f32_16x16x32_bf16 v[114:117], v[122:125], v[166:169], v[114:117]
	ds_read_b128 v[174:177], v187
	v_mfma_f32_16x16x32_bf16 v[82:85], v[126:129], v[166:169], v[82:85]
	ds_read_b128 v[170:173], v187 offset:1024
	v_mfma_f32_16x16x32_bf16 v[50:53], v[130:133], v[166:169], v[50:53]
	ds_read_b128 v[162:165], v187 offset:3072
	v_mfma_f32_16x16x32_bf16 v[18:21], v[134:137], v[166:169], v[18:21]
	ds_read_b128 v[166:169], v187 offset:2048
	v_mfma_f32_16x16x32_bf16 v[106:109], v[122:125], v[232:235], v[106:109]
	v_mfma_f32_16x16x32_bf16 v[74:77], v[126:129], v[232:235], v[74:77]
	v_mfma_f32_16x16x32_bf16 v[42:45], v[130:133], v[232:235], v[42:45]
	v_mfma_f32_16x16x32_bf16 v[10:13], v[134:137], v[232:235], v[10:13]
	v_mfma_f32_16x16x32_bf16 v[98:101], v[122:125], v[236:239], v[98:101]
	v_mfma_f32_16x16x32_bf16 v[66:69], v[126:129], v[236:239], v[66:69]
	v_mfma_f32_16x16x32_bf16 v[34:37], v[130:133], v[236:239], v[34:37]
	v_mfma_f32_16x16x32_bf16 v[2:5], v[134:137], v[236:239], v[2:5]
	s_waitcnt vmcnt(4)
	s_waitcnt lgkmcnt(0)
	s_barrier
	v_mfma_f32_16x16x32_bf16 v[158:161], v[174:177], v[150:153], v[158:161]
	v_mfma_f32_16x16x32_bf16 v[94:97], v[170:173], v[150:153], v[94:97]
	v_add_u32_e32 v226, s35, v230
	ds_read_b128 v[232:235], v226
	v_mfma_f32_16x16x32_bf16 v[62:65], v[166:169], v[150:153], v[62:65]
	ds_read_b128 v[236:239], v226 offset:1024
	v_mfma_f32_16x16x32_bf16 v[30:33], v[162:165], v[150:153], v[30:33]
	ds_read_b128 v[182:185], v226 offset:2048
	v_mfma_f32_16x16x32_bf16 v[118:121], v[174:177], v[146:149], v[118:121]
	ds_read_b128 v[178:181], v226 offset:3072
	v_mfma_f32_16x16x32_bf16 v[86:89], v[170:173], v[146:149], v[86:89]
	v_mfma_f32_16x16x32_bf16 v[54:57], v[166:169], v[146:149], v[54:57]
	v_mfma_f32_16x16x32_bf16 v[22:25], v[162:165], v[146:149], v[22:25]
	v_mfma_f32_16x16x32_bf16 v[110:113], v[174:177], v[142:145], v[110:113]
	v_mfma_f32_16x16x32_bf16 v[78:81], v[170:173], v[142:145], v[78:81]
	v_mfma_f32_16x16x32_bf16 v[46:49], v[166:169], v[142:145], v[46:49]
	v_mfma_f32_16x16x32_bf16 v[14:17], v[162:165], v[142:145], v[14:17]
	v_mfma_f32_16x16x32_bf16 v[102:105], v[174:177], v[138:141], v[102:105]
	v_mfma_f32_16x16x32_bf16 v[70:73], v[170:173], v[138:141], v[70:73]
	v_mfma_f32_16x16x32_bf16 v[38:41], v[166:169], v[138:141], v[38:41]
	v_mfma_f32_16x16x32_bf16 v[6:9], v[162:165], v[138:141], v[6:9]
	s_waitcnt lgkmcnt(0)
	v_mfma_f32_16x16x32_bf16 v[154:157], v[174:177], v[232:235], v[154:157]
	s_add_i32 s24, s31, 0xffff8000
	s_and_b32 s24, s24, 0x10000
	v_add_u32_e32 v187, s24, v200
	v_add_u32_e32 v226, s24, v201
	ds_read_b128 v[150:153], v226
	v_mfma_f32_16x16x32_bf16 v[90:93], v[170:173], v[232:235], v[90:93]
	ds_read_b128 v[146:149], v226 offset:1024
	v_mfma_f32_16x16x32_bf16 v[58:61], v[166:169], v[232:235], v[58:61]
	ds_read_b128 v[142:145], v226 offset:2048
	v_mfma_f32_16x16x32_bf16 v[26:29], v[162:165], v[232:235], v[26:29]
	ds_read_b128 v[138:141], v226 offset:3072
	v_mfma_f32_16x16x32_bf16 v[114:117], v[174:177], v[236:239], v[114:117]
	ds_read_b128 v[122:125], v187
	v_mfma_f32_16x16x32_bf16 v[82:85], v[170:173], v[236:239], v[82:85]
	ds_read_b128 v[126:129], v187 offset:1024
	v_mfma_f32_16x16x32_bf16 v[50:53], v[166:169], v[236:239], v[50:53]
	ds_read_b128 v[130:133], v187 offset:2048
	v_mfma_f32_16x16x32_bf16 v[18:21], v[162:165], v[236:239], v[18:21]
	ds_read_b128 v[134:137], v187 offset:3072
	s_add_i32 s19, s19, 2
	s_add_u32 s20, s20, 0x80
	s_addc_u32 s21, s21, 0
	s_add_i32 s31, s31, 0x10000
	v_mfma_f32_16x16x32_bf16 v[106:109], v[174:177], v[182:185], v[106:109]
	v_mfma_f32_16x16x32_bf16 v[74:77], v[170:173], v[182:185], v[74:77]
	v_mfma_f32_16x16x32_bf16 v[42:45], v[166:169], v[182:185], v[42:45]
	v_mfma_f32_16x16x32_bf16 v[10:13], v[162:165], v[182:185], v[10:13]
	v_mfma_f32_16x16x32_bf16 v[98:101], v[174:177], v[178:181], v[98:101]
	v_mfma_f32_16x16x32_bf16 v[66:69], v[170:173], v[178:181], v[66:69]
	v_mfma_f32_16x16x32_bf16 v[34:37], v[166:169], v[178:181], v[34:37]
	v_mfma_f32_16x16x32_bf16 v[2:5], v[162:165], v[178:181], v[2:5]
	s_waitcnt vmcnt(0)
	s_waitcnt lgkmcnt(0)
	s_barrier
	v_mfma_f32_16x16x32_bf16 v[158:161], v[122:125], v[150:153], v[158:161]
	v_mfma_f32_16x16x32_bf16 v[94:97], v[126:129], v[150:153], v[94:97]
	s_add_i32 s28, s31, 0xfffe8000
	s_and_b32 s34, s28, 0x10000
	v_add_u32_e32 v170, s34, v230
	ds_read_b128 v[162:165], v170
	v_mfma_f32_16x16x32_bf16 v[62:65], v[130:133], v[150:153], v[62:65]
	ds_read_b128 v[166:169], v170 offset:1024
	v_mfma_f32_16x16x32_bf16 v[30:33], v[134:137], v[150:153], v[30:33]
	ds_read_b128 v[232:235], v170 offset:2048
	v_mfma_f32_16x16x32_bf16 v[118:121], v[122:125], v[146:149], v[118:121]
	ds_read_b128 v[236:239], v170 offset:3072
	v_mfma_f32_16x16x32_bf16 v[86:89], v[126:129], v[146:149], v[86:89]
	v_mfma_f32_16x16x32_bf16 v[54:57], v[130:133], v[146:149], v[54:57]
	v_mfma_f32_16x16x32_bf16 v[22:25], v[134:137], v[146:149], v[22:25]
	v_mfma_f32_16x16x32_bf16 v[110:113], v[122:125], v[142:145], v[110:113]
	v_mfma_f32_16x16x32_bf16 v[78:81], v[126:129], v[142:145], v[78:81]
	v_mfma_f32_16x16x32_bf16 v[46:49], v[130:133], v[142:145], v[46:49]
	v_mfma_f32_16x16x32_bf16 v[14:17], v[134:137], v[142:145], v[14:17]
	v_mfma_f32_16x16x32_bf16 v[102:105], v[122:125], v[138:141], v[102:105]
	v_mfma_f32_16x16x32_bf16 v[70:73], v[126:129], v[138:141], v[70:73]
	v_mfma_f32_16x16x32_bf16 v[38:41], v[130:133], v[138:141], v[38:41]
	v_mfma_f32_16x16x32_bf16 v[6:9], v[134:137], v[138:141], v[6:9]
	s_waitcnt lgkmcnt(0)
	v_mfma_f32_16x16x32_bf16 v[154:157], v[122:125], v[162:165], v[154:157]
	s_add_i32 s28, s31, 0xffff0000
	s_and_b32 s35, s28, 0x18000
	v_add_u32_e32 v187, s35, v200
	v_add_u32_e32 v226, s35, v201
	ds_read_b128 v[150:153], v226
	v_mfma_f32_16x16x32_bf16 v[90:93], v[126:129], v[162:165], v[90:93]
	ds_read_b128 v[146:149], v226 offset:1024
	v_mfma_f32_16x16x32_bf16 v[58:61], v[130:133], v[162:165], v[58:61]
	ds_read_b128 v[142:145], v226 offset:2048
	v_mfma_f32_16x16x32_bf16 v[26:29], v[134:137], v[162:165], v[26:29]
	ds_read_b128 v[138:141], v226 offset:3072
	v_mfma_f32_16x16x32_bf16 v[114:117], v[122:125], v[166:169], v[114:117]
	ds_read_b128 v[174:177], v187
	v_mfma_f32_16x16x32_bf16 v[82:85], v[126:129], v[166:169], v[82:85]
	ds_read_b128 v[170:173], v187 offset:1024
	v_mfma_f32_16x16x32_bf16 v[50:53], v[130:133], v[166:169], v[50:53]
	ds_read_b128 v[162:165], v187 offset:3072
	v_mfma_f32_16x16x32_bf16 v[18:21], v[134:137], v[166:169], v[18:21]
	ds_read_b128 v[166:169], v187 offset:2048
	v_mfma_f32_16x16x32_bf16 v[106:109], v[122:125], v[232:235], v[106:109]
	v_mfma_f32_16x16x32_bf16 v[74:77], v[126:129], v[232:235], v[74:77]
	v_mfma_f32_16x16x32_bf16 v[42:45], v[130:133], v[232:235], v[42:45]
	v_mfma_f32_16x16x32_bf16 v[10:13], v[134:137], v[232:235], v[10:13]
	v_mfma_f32_16x16x32_bf16 v[98:101], v[122:125], v[236:239], v[98:101]
	v_mfma_f32_16x16x32_bf16 v[66:69], v[126:129], v[236:239], v[66:69]
	v_mfma_f32_16x16x32_bf16 v[34:37], v[130:133], v[236:239], v[34:37]
	v_mfma_f32_16x16x32_bf16 v[2:5], v[134:137], v[236:239], v[2:5]
	s_waitcnt vmcnt(0)
	s_waitcnt lgkmcnt(0)
	s_barrier
	v_mfma_f32_16x16x32_bf16 v[158:161], v[174:177], v[150:153], v[158:161]
	v_mfma_f32_16x16x32_bf16 v[94:97], v[170:173], v[150:153], v[94:97]
	v_add_u32_e32 v226, s35, v230
	ds_read_b128 v[232:235], v226
	v_mfma_f32_16x16x32_bf16 v[62:65], v[166:169], v[150:153], v[62:65]
	ds_read_b128 v[236:239], v226 offset:1024
	v_mfma_f32_16x16x32_bf16 v[30:33], v[162:165], v[150:153], v[30:33]
	ds_read_b128 v[182:185], v226 offset:2048
	v_mfma_f32_16x16x32_bf16 v[118:121], v[174:177], v[146:149], v[118:121]
	ds_read_b128 v[178:181], v226 offset:3072
	v_mfma_f32_16x16x32_bf16 v[86:89], v[170:173], v[146:149], v[86:89]
	v_mfma_f32_16x16x32_bf16 v[54:57], v[166:169], v[146:149], v[54:57]
	v_mfma_f32_16x16x32_bf16 v[22:25], v[162:165], v[146:149], v[22:25]
	v_mfma_f32_16x16x32_bf16 v[110:113], v[174:177], v[142:145], v[110:113]
	v_mfma_f32_16x16x32_bf16 v[78:81], v[170:173], v[142:145], v[78:81]
	v_mfma_f32_16x16x32_bf16 v[46:49], v[166:169], v[142:145], v[46:49]
	v_mfma_f32_16x16x32_bf16 v[14:17], v[162:165], v[142:145], v[14:17]
	v_mfma_f32_16x16x32_bf16 v[102:105], v[174:177], v[138:141], v[102:105]
	v_mfma_f32_16x16x32_bf16 v[70:73], v[170:173], v[138:141], v[70:73]
	v_mfma_f32_16x16x32_bf16 v[38:41], v[166:169], v[138:141], v[38:41]
	v_mfma_f32_16x16x32_bf16 v[6:9], v[162:165], v[138:141], v[6:9]
	s_waitcnt lgkmcnt(0)
	v_mfma_f32_16x16x32_bf16 v[154:157], v[174:177], v[232:235], v[154:157]
	v_mfma_f32_16x16x32_bf16 v[90:93], v[170:173], v[232:235], v[90:93]
	v_mfma_f32_16x16x32_bf16 v[58:61], v[166:169], v[232:235], v[58:61]
	v_mfma_f32_16x16x32_bf16 v[26:29], v[162:165], v[232:235], v[26:29]
	v_mfma_f32_16x16x32_bf16 v[114:117], v[174:177], v[236:239], v[114:117]
	v_mfma_f32_16x16x32_bf16 v[82:85], v[170:173], v[236:239], v[82:85]
	v_mfma_f32_16x16x32_bf16 v[50:53], v[166:169], v[236:239], v[50:53]
	v_mfma_f32_16x16x32_bf16 v[18:21], v[162:165], v[236:239], v[18:21]
	s_add_i32 s19, s19, 2
	s_add_u32 s20, s20, 0x80
	s_addc_u32 s21, s21, 0
	s_add_i32 s31, s31, 0x10000
	v_mfma_f32_16x16x32_bf16 v[106:109], v[174:177], v[182:185], v[106:109]
	v_mfma_f32_16x16x32_bf16 v[74:77], v[170:173], v[182:185], v[74:77]
	v_mfma_f32_16x16x32_bf16 v[42:45], v[166:169], v[182:185], v[42:45]
	v_mfma_f32_16x16x32_bf16 v[10:13], v[162:165], v[182:185], v[10:13]
	v_mfma_f32_16x16x32_bf16 v[98:101], v[174:177], v[178:181], v[98:101]
	v_mfma_f32_16x16x32_bf16 v[66:69], v[170:173], v[178:181], v[66:69]
	v_mfma_f32_16x16x32_bf16 v[34:37], v[166:169], v[178:181], v[34:37]
	v_mfma_f32_16x16x32_bf16 v[2:5], v[162:165], v[178:181], v[2:5]
	s_branch .LBB0_197
.Lgr_G4x_entry:
	s_waitcnt vmcnt(4)
	s_waitcnt lgkmcnt(0)
	s_barrier
	v_mfma_f32_16x16x32_bf16 v[158:161], v[122:125], v[150:153], v[158:161]
	v_mfma_f32_16x16x32_bf16 v[94:97], v[126:129], v[150:153], v[94:97]
	s_add_i32 s28, s31, 0xfffe8000
	s_and_b32 s34, s28, 0x10000
	v_add_u32_e32 v170, s34, v230
	ds_read_b128 v[162:165], v170
	v_mfma_f32_16x16x32_bf16 v[62:65], v[130:133], v[150:153], v[62:65]
	ds_read_b128 v[166:169], v170 offset:1024
	v_mfma_f32_16x16x32_bf16 v[30:33], v[134:137], v[150:153], v[30:33]
	ds_read_b128 v[232:235], v170 offset:2048
	v_mfma_f32_16x16x32_bf16 v[118:121], v[122:125], v[146:149], v[118:121]
	ds_read_b128 v[236:239], v170 offset:3072
	s_and_b32 s89, s31, 0x18000
	s_add_i32 s89, s89, s88
	s_mov_b32 m0, s89
	v_mfma_f32_16x16x32_bf16 v[86:89], v[126:129], v[146:149], v[86:89]
	v_mfma_f32_16x16x32_bf16 v[54:57], v[130:133], v[146:149], v[54:57]
	v_mfma_f32_16x16x32_bf16 v[22:25], v[134:137], v[146:149], v[22:25]
	global_load_lds_dwordx4 v186, s[90:91]
	s_add_i32 m0, s89, 0x2000
	v_mfma_f32_16x16x32_bf16 v[110:113], v[122:125], v[142:145], v[110:113]
	v_mfma_f32_16x16x32_bf16 v[78:81], v[126:129], v[142:145], v[78:81]
	v_mfma_f32_16x16x32_bf16 v[46:49], v[130:133], v[142:145], v[46:49]
	global_load_lds_dwordx4 v188, s[90:91]
	s_add_i32 m0, s89, 0x4000
	v_mfma_f32_16x16x32_bf16 v[14:17], v[134:137], v[142:145], v[14:17]
	v_mfma_f32_16x16x32_bf16 v[102:105], v[122:125], v[138:141], v[102:105]
	global_load_lds_dwordx4 v190, s[92:93]
	s_add_i32 m0, s89, 0x6000
	v_mfma_f32_16x16x32_bf16 v[70:73], v[126:129], v[138:141], v[70:73]
	global_load_lds_dwordx4 v192, s[92:93]
	s_add_u32 s90, s90, 64
	s_addc_u32 s91, s91, 0
	s_add_u32 s92, s92, 64
	s_addc_u32 s93, s93, 0
	v_mfma_f32_16x16x32_bf16 v[38:41], v[130:133], v[138:141], v[38:41]
	v_mfma_f32_16x16x32_bf16 v[6:9], v[134:137], v[138:141], v[6:9]
	s_waitcnt vmcnt(4)
	s_waitcnt lgkmcnt(0)
	s_barrier
	v_mfma_f32_16x16x32_bf16 v[154:157], v[122:125], v[162:165], v[154:157]
	s_add_i32 s28, s31, 0xffff0000
	s_and_b32 s35, s28, 0x18000
	v_add_u32_e32 v187, s35, v200
	v_add_u32_e32 v226, s35, v201
	ds_read_b128 v[150:153], v226
	v_mfma_f32_16x16x32_bf16 v[90:93], v[126:129], v[162:165], v[90:93]
	ds_read_b128 v[146:149], v226 offset:1024
	v_mfma_f32_16x16x32_bf16 v[58:61], v[130:133], v[162:165], v[58:61]
	ds_read_b128 v[142:145], v226 offset:2048
	v_mfma_f32_16x16x32_bf16 v[26:29], v[134:137], v[162:165], v[26:29]
	ds_read_b128 v[138:141], v226 offset:3072
	v_mfma_f32_16x16x32_bf16 v[114:117], v[122:125], v[166:169], v[114:117]
	ds_read_b128 v[174:177], v187
	v_mfma_f32_16x16x32_bf16 v[82:85], v[126:129], v[166:169], v[82:85]
	ds_read_b128 v[170:173], v187 offset:1024
	v_mfma_f32_16x16x32_bf16 v[50:53], v[130:133], v[166:169], v[50:53]
	ds_read_b128 v[162:165], v187 offset:3072
	v_mfma_f32_16x16x32_bf16 v[18:21], v[134:137], v[166:169], v[18:21]
	ds_read_b128 v[166:169], v187 offset:2048
	v_mfma_f32_16x16x32_bf16 v[106:109], v[122:125], v[232:235], v[106:109]
	v_mfma_f32_16x16x32_bf16 v[74:77], v[126:129], v[232:235], v[74:77]
	v_mfma_f32_16x16x32_bf16 v[42:45], v[130:133], v[232:235], v[42:45]
	v_mfma_f32_16x16x32_bf16 v[10:13], v[134:137], v[232:235], v[10:13]
	v_mfma_f32_16x16x32_bf16 v[98:101], v[122:125], v[236:239], v[98:101]
	v_mfma_f32_16x16x32_bf16 v[66:69], v[126:129], v[236:239], v[66:69]
	v_mfma_f32_16x16x32_bf16 v[34:37], v[130:133], v[236:239], v[34:37]
	v_mfma_f32_16x16x32_bf16 v[2:5], v[134:137], v[236:239], v[2:5]
	s_waitcnt lgkmcnt(0)
	v_mfma_f32_16x16x32_bf16 v[158:161], v[174:177], v[150:153], v[158:161]
	v_mfma_f32_16x16x32_bf16 v[94:97], v[170:173], v[150:153], v[94:97]
	v_add_u32_e32 v226, s35, v230
	ds_read_b128 v[232:235], v226
	v_mfma_f32_16x16x32_bf16 v[62:65], v[166:169], v[150:153], v[62:65]
	ds_read_b128 v[236:239], v226 offset:1024
	v_mfma_f32_16x16x32_bf16 v[30:33], v[162:165], v[150:153], v[30:33]
	ds_read_b128 v[182:185], v226 offset:2048
	v_mfma_f32_16x16x32_bf16 v[118:121], v[174:177], v[146:149], v[118:121]
	ds_read_b128 v[178:181], v226 offset:3072
	s_add_i32 s89, s34, s88
	s_mov_b32 m0, s89
	v_mfma_f32_16x16x32_bf16 v[86:89], v[170:173], v[146:149], v[86:89]
	v_mfma_f32_16x16x32_bf16 v[54:57], v[166:169], v[146:149], v[54:57]
	v_mfma_f32_16x16x32_bf16 v[22:25], v[162:165], v[146:149], v[22:25]
	global_load_lds_dwordx4 v186, s[90:91]
	s_add_i32 m0, s89, 0x2000
	v_mfma_f32_16x16x32_bf16 v[110:113], v[174:177], v[142:145], v[110:113]
	v_mfma_f32_16x16x32_bf16 v[78:81], v[170:173], v[142:145], v[78:81]
	v_mfma_f32_16x16x32_bf16 v[46:49], v[166:169], v[142:145], v[46:49]
	global_load_lds_dwordx4 v188, s[90:91]
	s_add_i32 m0, s89, 0x4000
	v_mfma_f32_16x16x32_bf16 v[14:17], v[162:165], v[142:145], v[14:17]
	v_mfma_f32_16x16x32_bf16 v[102:105], v[174:177], v[138:141], v[102:105]
	global_load_lds_dwordx4 v190, s[92:93]
	s_add_i32 m0, s89, 0x6000
	v_mfma_f32_16x16x32_bf16 v[70:73], v[170:173], v[138:141], v[70:73]
	global_load_lds_dwordx4 v192, s[92:93]
	s_add_u32 s90, s90, 64
	s_addc_u32 s91, s91, 0
	s_add_u32 s92, s92, 64
	s_addc_u32 s93, s93, 0
	v_mfma_f32_16x16x32_bf16 v[38:41], v[166:169], v[138:141], v[38:41]
	v_mfma_f32_16x16x32_bf16 v[6:9], v[162:165], v[138:141], v[6:9]
.Lgr_G4x_top:
	s_waitcnt vmcnt(4)
	s_waitcnt lgkmcnt(0)
	s_barrier
	v_mfma_f32_16x16x32_bf16 v[154:157], v[174:177], v[232:235], v[154:157]
	s_add_i32 s24, s31, 0xffff8000
	s_and_b32 s24, s24, 0x10000
	v_add_u32_e32 v187, s24, v200
	v_add_u32_e32 v226, s24, v201
	ds_read_b128 v[150:153], v226
	v_mfma_f32_16x16x32_bf16 v[90:93], v[170:173], v[232:235], v[90:93]
	ds_read_b128 v[146:149], v226 offset:1024
	v_mfma_f32_16x16x32_bf16 v[58:61], v[166:169], v[232:235], v[58:61]
	ds_read_b128 v[142:145], v226 offset:2048
	v_mfma_f32_16x16x32_bf16 v[26:29], v[162:165], v[232:235], v[26:29]
	ds_read_b128 v[138:141], v226 offset:3072
	v_mfma_f32_16x16x32_bf16 v[114:117], v[174:177], v[236:239], v[114:117]
	ds_read_b128 v[122:125], v187
	v_mfma_f32_16x16x32_bf16 v[82:85], v[170:173], v[236:239], v[82:85]
	ds_read_b128 v[126:129], v187 offset:1024
	v_mfma_f32_16x16x32_bf16 v[50:53], v[166:169], v[236:239], v[50:53]
	ds_read_b128 v[130:133], v187 offset:2048
	v_mfma_f32_16x16x32_bf16 v[18:21], v[162:165], v[236:239], v[18:21]
	ds_read_b128 v[134:137], v187 offset:3072
	s_add_i32 s19, s19, 2
	s_add_u32 s20, s20, 0x80
	s_addc_u32 s21, s21, 0
	s_add_i32 s31, s31, 0x10000
	v_mfma_f32_16x16x32_bf16 v[106:109], v[174:177], v[182:185], v[106:109]
	v_mfma_f32_16x16x32_bf16 v[74:77], v[170:173], v[182:185], v[74:77]
	v_mfma_f32_16x16x32_bf16 v[42:45], v[166:169], v[182:185], v[42:45]
	v_mfma_f32_16x16x32_bf16 v[10:13], v[162:165], v[182:185], v[10:13]
	v_mfma_f32_16x16x32_bf16 v[98:101], v[174:177], v[178:181], v[98:101]
	v_mfma_f32_16x16x32_bf16 v[66:69], v[170:173], v[178:181], v[66:69]
	v_mfma_f32_16x16x32_bf16 v[34:37], v[166:169], v[178:181], v[34:37]
	v_mfma_f32_16x16x32_bf16 v[2:5], v[162:165], v[178:181], v[2:5]
	s_cmp_lt_u32 s19, 28
	s_cbranch_scc0 .Lgr_G4x_tail
	s_waitcnt lgkmcnt(0)
	v_mfma_f32_16x16x32_bf16 v[158:161], v[122:125], v[150:153], v[158:161]
	v_mfma_f32_16x16x32_bf16 v[94:97], v[126:129], v[150:153], v[94:97]
	s_add_i32 s28, s31, 0xfffe8000
	s_and_b32 s34, s28, 0x10000
	v_add_u32_e32 v170, s34, v230
	ds_read_b128 v[162:165], v170
	v_mfma_f32_16x16x32_bf16 v[62:65], v[130:133], v[150:153], v[62:65]
	ds_read_b128 v[166:169], v170 offset:1024
	v_mfma_f32_16x16x32_bf16 v[30:33], v[134:137], v[150:153], v[30:33]
	ds_read_b128 v[232:235], v170 offset:2048
	v_mfma_f32_16x16x32_bf16 v[118:121], v[122:125], v[146:149], v[118:121]
	ds_read_b128 v[236:239], v170 offset:3072
	s_and_b32 s89, s31, 0x18000
	s_add_i32 s89, s89, s88
	s_mov_b32 m0, s89
	v_mfma_f32_16x16x32_bf16 v[86:89], v[126:129], v[146:149], v[86:89]
	v_mfma_f32_16x16x32_bf16 v[54:57], v[130:133], v[146:149], v[54:57]
	v_mfma_f32_16x16x32_bf16 v[22:25], v[134:137], v[146:149], v[22:25]
	global_load_lds_dwordx4 v186, s[90:91]
	s_add_i32 m0, s89, 0x2000
	v_mfma_f32_16x16x32_bf16 v[110:113], v[122:125], v[142:145], v[110:113]
	v_mfma_f32_16x16x32_bf16 v[78:81], v[126:129], v[142:145], v[78:81]
	v_mfma_f32_16x16x32_bf16 v[46:49], v[130:133], v[142:145], v[46:49]
	global_load_lds_dwordx4 v188, s[90:91]
	s_add_i32 m0, s89, 0x4000
	v_mfma_f32_16x16x32_bf16 v[14:17], v[134:137], v[142:145], v[14:17]
	v_mfma_f32_16x16x32_bf16 v[102:105], v[122:125], v[138:141], v[102:105]
	global_load_lds_dwordx4 v190, s[92:93]
	s_add_i32 m0, s89, 0x6000
	v_mfma_f32_16x16x32_bf16 v[70:73], v[126:129], v[138:141], v[70:73]
	global_load_lds_dwordx4 v192, s[92:93]
	s_add_u32 s90, s90, 64
	s_addc_u32 s91, s91, 0
	s_add_u32 s92, s92, 64
	s_addc_u32 s93, s93, 0
	v_mfma_f32_16x16x32_bf16 v[38:41], v[130:133], v[138:141], v[38:41]
	v_mfma_f32_16x16x32_bf16 v[6:9], v[134:137], v[138:141], v[6:9]
	s_waitcnt vmcnt(4)
	s_waitcnt lgkmcnt(0)
	s_barrier
	v_mfma_f32_16x16x32_bf16 v[154:157], v[122:125], v[162:165], v[154:157]
	s_add_i32 s28, s31, 0xffff0000
	s_and_b32 s35, s28, 0x18000
	v_add_u32_e32 v187, s35, v200
	v_add_u32_e32 v226, s35, v201
	ds_read_b128 v[150:153], v226
	v_mfma_f32_16x16x32_bf16 v[90:93], v[126:129], v[162:165], v[90:93]
	ds_read_b128 v[146:149], v226 offset:1024
	v_mfma_f32_16x16x32_bf16 v[58:61], v[130:133], v[162:165], v[58:61]
	ds_read_b128 v[142:145], v226 offset:2048
	v_mfma_f32_16x16x32_bf16 v[26:29], v[134:137], v[162:165], v[26:29]
	ds_read_b128 v[138:141], v226 offset:3072
	v_mfma_f32_16x16x32_bf16 v[114:117], v[122:125], v[166:169], v[114:117]
	ds_read_b128 v[174:177], v187
	v_mfma_f32_16x16x32_bf16 v[82:85], v[126:129], v[166:169], v[82:85]
	ds_read_b128 v[170:173], v187 offset:1024
	v_mfma_f32_16x16x32_bf16 v[50:53], v[130:133], v[166:169], v[50:53]
	ds_read_b128 v[162:165], v187 offset:3072
	v_mfma_f32_16x16x32_bf16 v[18:21], v[134:137], v[166:169], v[18:21]
	ds_read_b128 v[166:169], v187 offset:2048
	v_mfma_f32_16x16x32_bf16 v[106:109], v[122:125], v[232:235], v[106:109]
	v_mfma_f32_16x16x32_bf16 v[74:77], v[126:129], v[232:235], v[74:77]
	v_mfma_f32_16x16x32_bf16 v[42:45], v[130:133], v[232:235], v[42:45]
	v_mfma_f32_16x16x32_bf16 v[10:13], v[134:137], v[232:235], v[10:13]
	v_mfma_f32_16x16x32_bf16 v[98:101], v[122:125], v[236:239], v[98:101]
	v_mfma_f32_16x16x32_bf16 v[66:69], v[126:129], v[236:239], v[66:69]
	v_mfma_f32_16x16x32_bf16 v[34:37], v[130:133], v[236:239], v[34:37]
	v_mfma_f32_16x16x32_bf16 v[2:5], v[134:137], v[236:239], v[2:5]
	s_waitcnt lgkmcnt(0)
	v_mfma_f32_16x16x32_bf16 v[158:161], v[174:177], v[150:153], v[158:161]
	v_mfma_f32_16x16x32_bf16 v[94:97], v[170:173], v[150:153], v[94:97]
	v_add_u32_e32 v226, s35, v230
	ds_read_b128 v[232:235], v226
	v_mfma_f32_16x16x32_bf16 v[62:65], v[166:169], v[150:153], v[62:65]
	ds_read_b128 v[236:239], v226 offset:1024
	v_mfma_f32_16x16x32_bf16 v[30:33], v[162:165], v[150:153], v[30:33]
	ds_read_b128 v[182:185], v226 offset:2048
	v_mfma_f32_16x16x32_bf16 v[118:121], v[174:177], v[146:149], v[118:121]
	ds_read_b128 v[178:181], v226 offset:3072
	s_add_i32 s89, s34, s88
	s_mov_b32 m0, s89
	v_mfma_f32_16x16x32_bf16 v[86:89], v[170:173], v[146:149], v[86:89]
	v_mfma_f32_16x16x32_bf16 v[54:57], v[166:169], v[146:149], v[54:57]
	v_mfma_f32_16x16x32_bf16 v[22:25], v[162:165], v[146:149], v[22:25]
	global_load_lds_dwordx4 v186, s[90:91]
	s_add_i32 m0, s89, 0x2000
	v_mfma_f32_16x16x32_bf16 v[110:113], v[174:177], v[142:145], v[110:113]
	v_mfma_f32_16x16x32_bf16 v[78:81], v[170:173], v[142:145], v[78:81]
	v_mfma_f32_16x16x32_bf16 v[46:49], v[166:169], v[142:145], v[46:49]
	global_load_lds_dwordx4 v188, s[90:91]
	s_add_i32 m0, s89, 0x4000
	v_mfma_f32_16x16x32_bf16 v[14:17], v[162:165], v[142:145], v[14:17]
	v_mfma_f32_16x16x32_bf16 v[102:105], v[174:177], v[138:141], v[102:105]
	global_load_lds_dwordx4 v190, s[92:93]
	s_add_i32 m0, s89, 0x6000
	v_mfma_f32_16x16x32_bf16 v[70:73], v[170:173], v[138:141], v[70:73]
	global_load_lds_dwordx4 v192, s[92:93]
	s_add_u32 s90, s90, 64
	s_addc_u32 s91, s91, 0
	s_add_u32 s92, s92, 64
	s_addc_u32 s93, s93, 0
	v_mfma_f32_16x16x32_bf16 v[38:41], v[166:169], v[138:141], v[38:41]
	v_mfma_f32_16x16x32_bf16 v[6:9], v[162:165], v[138:141], v[6:9]
	s_branch .Lgr_G4x_top
.Lgr_G4x_tail:
	s_waitcnt lgkmcnt(0)
	v_mfma_f32_16x16x32_bf16 v[158:161], v[122:125], v[150:153], v[158:161]
	v_mfma_f32_16x16x32_bf16 v[94:97], v[126:129], v[150:153], v[94:97]
	s_add_i32 s28, s31, 0xfffe8000
	s_and_b32 s34, s28, 0x10000
	v_add_u32_e32 v170, s34, v230
	ds_read_b128 v[162:165], v170
	v_mfma_f32_16x16x32_bf16 v[62:65], v[130:133], v[150:153], v[62:65]
	ds_read_b128 v[166:169], v170 offset:1024
	v_mfma_f32_16x16x32_bf16 v[30:33], v[134:137], v[150:153], v[30:33]
	ds_read_b128 v[232:235], v170 offset:2048
	v_mfma_f32_16x16x32_bf16 v[118:121], v[122:125], v[146:149], v[118:121]
	ds_read_b128 v[236:239], v170 offset:3072
	s_and_b32 s89, s31, 0x18000
	s_add_i32 s89, s89, s88
	s_mov_b32 m0, s89
	v_mfma_f32_16x16x32_bf16 v[86:89], v[126:129], v[146:149], v[86:89]
	v_mfma_f32_16x16x32_bf16 v[54:57], v[130:133], v[146:149], v[54:57]
	v_mfma_f32_16x16x32_bf16 v[22:25], v[134:137], v[146:149], v[22:25]
	global_load_lds_dwordx4 v186, s[90:91]
	s_add_i32 m0, s89, 0x2000
	v_mfma_f32_16x16x32_bf16 v[110:113], v[122:125], v[142:145], v[110:113]
	v_mfma_f32_16x16x32_bf16 v[78:81], v[126:129], v[142:145], v[78:81]
	v_mfma_f32_16x16x32_bf16 v[46:49], v[130:133], v[142:145], v[46:49]
	global_load_lds_dwordx4 v188, s[90:91]
	s_add_i32 m0, s89, 0x4000
	v_mfma_f32_16x16x32_bf16 v[14:17], v[134:137], v[142:145], v[14:17]
	v_mfma_f32_16x16x32_bf16 v[102:105], v[122:125], v[138:141], v[102:105]
	global_load_lds_dwordx4 v190, s[92:93]
	s_add_i32 m0, s89, 0x6000
	v_mfma_f32_16x16x32_bf16 v[70:73], v[126:129], v[138:141], v[70:73]
	global_load_lds_dwordx4 v192, s[92:93]
	s_add_u32 s90, s90, 64
	s_addc_u32 s91, s91, 0
	s_add_u32 s92, s92, 64
	s_addc_u32 s93, s93, 0
	v_mfma_f32_16x16x32_bf16 v[38:41], v[130:133], v[138:141], v[38:41]
	v_mfma_f32_16x16x32_bf16 v[6:9], v[134:137], v[138:141], v[6:9]
	s_waitcnt vmcnt(4)
	s_waitcnt lgkmcnt(0)
	s_barrier
	v_mfma_f32_16x16x32_bf16 v[154:157], v[122:125], v[162:165], v[154:157]
	s_add_i32 s28, s31, 0xffff0000
	s_and_b32 s35, s28, 0x18000
	v_add_u32_e32 v187, s35, v200
	v_add_u32_e32 v226, s35, v201
	ds_read_b128 v[150:153], v226
	v_mfma_f32_16x16x32_bf16 v[90:93], v[126:129], v[162:165], v[90:93]
	ds_read_b128 v[146:149], v226 offset:1024
	v_mfma_f32_16x16x32_bf16 v[58:61], v[130:133], v[162:165], v[58:61]
	ds_read_b128 v[142:145], v226 offset:2048
	v_mfma_f32_16x16x32_bf16 v[26:29], v[134:137], v[162:165], v[26:29]
	ds_read_b128 v[138:141], v226 offset:3072
	v_mfma_f32_16x16x32_bf16 v[114:117], v[122:125], v[166:169], v[114:117]
	ds_read_b128 v[174:177], v187
	v_mfma_f32_16x16x32_bf16 v[82:85], v[126:129], v[166:169], v[82:85]
	ds_read_b128 v[170:173], v187 offset:1024
	v_mfma_f32_16x16x32_bf16 v[50:53], v[130:133], v[166:169], v[50:53]
	ds_read_b128 v[162:165], v187 offset:3072
	v_mfma_f32_16x16x32_bf16 v[18:21], v[134:137], v[166:169], v[18:21]
	ds_read_b128 v[166:169], v187 offset:2048
	v_mfma_f32_16x16x32_bf16 v[106:109], v[122:125], v[232:235], v[106:109]
	v_mfma_f32_16x16x32_bf16 v[74:77], v[126:129], v[232:235], v[74:77]
	v_mfma_f32_16x16x32_bf16 v[42:45], v[130:133], v[232:235], v[42:45]
	v_mfma_f32_16x16x32_bf16 v[10:13], v[134:137], v[232:235], v[10:13]
	v_mfma_f32_16x16x32_bf16 v[98:101], v[122:125], v[236:239], v[98:101]
	v_mfma_f32_16x16x32_bf16 v[66:69], v[126:129], v[236:239], v[66:69]
	v_mfma_f32_16x16x32_bf16 v[34:37], v[130:133], v[236:239], v[34:37]
	v_mfma_f32_16x16x32_bf16 v[2:5], v[134:137], v[236:239], v[2:5]
	s_waitcnt lgkmcnt(0)
	v_mfma_f32_16x16x32_bf16 v[158:161], v[174:177], v[150:153], v[158:161]
	v_mfma_f32_16x16x32_bf16 v[94:97], v[170:173], v[150:153], v[94:97]
	v_add_u32_e32 v226, s35, v230
	ds_read_b128 v[232:235], v226
	v_mfma_f32_16x16x32_bf16 v[62:65], v[166:169], v[150:153], v[62:65]
	ds_read_b128 v[236:239], v226 offset:1024
	v_mfma_f32_16x16x32_bf16 v[30:33], v[162:165], v[150:153], v[30:33]
	ds_read_b128 v[182:185], v226 offset:2048
	v_mfma_f32_16x16x32_bf16 v[118:121], v[174:177], v[146:149], v[118:121]
	ds_read_b128 v[178:181], v226 offset:3072
	v_mfma_f32_16x16x32_bf16 v[86:89], v[170:173], v[146:149], v[86:89]
	v_mfma_f32_16x16x32_bf16 v[54:57], v[166:169], v[146:149], v[54:57]
	v_mfma_f32_16x16x32_bf16 v[22:25], v[162:165], v[146:149], v[22:25]
	v_mfma_f32_16x16x32_bf16 v[110:113], v[174:177], v[142:145], v[110:113]
	v_mfma_f32_16x16x32_bf16 v[78:81], v[170:173], v[142:145], v[78:81]
	v_mfma_f32_16x16x32_bf16 v[46:49], v[166:169], v[142:145], v[46:49]
	v_mfma_f32_16x16x32_bf16 v[14:17], v[162:165], v[142:145], v[14:17]
	v_mfma_f32_16x16x32_bf16 v[102:105], v[174:177], v[138:141], v[102:105]
	v_mfma_f32_16x16x32_bf16 v[70:73], v[170:173], v[138:141], v[70:73]
	v_mfma_f32_16x16x32_bf16 v[38:41], v[166:169], v[138:141], v[38:41]
	v_mfma_f32_16x16x32_bf16 v[6:9], v[162:165], v[138:141], v[6:9]
	s_waitcnt vmcnt(0)
	s_waitcnt lgkmcnt(0)
	s_barrier
	v_mfma_f32_16x16x32_bf16 v[154:157], v[174:177], v[232:235], v[154:157]
	s_add_i32 s24, s31, 0xffff8000
	s_and_b32 s24, s24, 0x10000
	v_add_u32_e32 v187, s24, v200
	v_add_u32_e32 v226, s24, v201
	ds_read_b128 v[150:153], v226
	v_mfma_f32_16x16x32_bf16 v[90:93], v[170:173], v[232:235], v[90:93]
	ds_read_b128 v[146:149], v226 offset:1024
	v_mfma_f32_16x16x32_bf16 v[58:61], v[166:169], v[232:235], v[58:61]
	ds_read_b128 v[142:145], v226 offset:2048
	v_mfma_f32_16x16x32_bf16 v[26:29], v[162:165], v[232:235], v[26:29]
	ds_read_b128 v[138:141], v226 offset:3072
	v_mfma_f32_16x16x32_bf16 v[114:117], v[174:177], v[236:239], v[114:117]
	ds_read_b128 v[122:125], v187
	v_mfma_f32_16x16x32_bf16 v[82:85], v[170:173], v[236:239], v[82:85]
	ds_read_b128 v[126:129], v187 offset:1024
	v_mfma_f32_16x16x32_bf16 v[50:53], v[166:169], v[236:239], v[50:53]
	ds_read_b128 v[130:133], v187 offset:2048
	v_mfma_f32_16x16x32_bf16 v[18:21], v[162:165], v[236:239], v[18:21]
	ds_read_b128 v[134:137], v187 offset:3072
	s_add_i32 s19, s19, 2
	s_add_u32 s20, s20, 0x80
	s_addc_u32 s21, s21, 0
	s_add_i32 s31, s31, 0x10000
	v_mfma_f32_16x16x32_bf16 v[106:109], v[174:177], v[182:185], v[106:109]
	v_mfma_f32_16x16x32_bf16 v[74:77], v[170:173], v[182:185], v[74:77]
	v_mfma_f32_16x16x32_bf16 v[42:45], v[166:169], v[182:185], v[42:45]
	v_mfma_f32_16x16x32_bf16 v[10:13], v[162:165], v[182:185], v[10:13]
	v_mfma_f32_16x16x32_bf16 v[98:101], v[174:177], v[178:181], v[98:101]
	v_mfma_f32_16x16x32_bf16 v[66:69], v[170:173], v[178:181], v[66:69]
	v_mfma_f32_16x16x32_bf16 v[34:37], v[166:169], v[178:181], v[34:37]
	v_mfma_f32_16x16x32_bf16 v[2:5], v[162:165], v[178:181], v[2:5]
	s_waitcnt lgkmcnt(0)
	v_mfma_f32_16x16x32_bf16 v[158:161], v[122:125], v[150:153], v[158:161]
	v_mfma_f32_16x16x32_bf16 v[94:97], v[126:129], v[150:153], v[94:97]
	s_add_i32 s28, s31, 0xfffe8000
	s_and_b32 s34, s28, 0x10000
	v_add_u32_e32 v170, s34, v230
	ds_read_b128 v[162:165], v170
	v_mfma_f32_16x16x32_bf16 v[62:65], v[130:133], v[150:153], v[62:65]
	ds_read_b128 v[166:169], v170 offset:1024
	v_mfma_f32_16x16x32_bf16 v[30:33], v[134:137], v[150:153], v[30:33]
	ds_read_b128 v[232:235], v170 offset:2048
	v_mfma_f32_16x16x32_bf16 v[118:121], v[122:125], v[146:149], v[118:121]
	ds_read_b128 v[236:239], v170 offset:3072
	v_mfma_f32_16x16x32_bf16 v[86:89], v[126:129], v[146:149], v[86:89]
	v_mfma_f32_16x16x32_bf16 v[54:57], v[130:133], v[146:149], v[54:57]
	v_mfma_f32_16x16x32_bf16 v[22:25], v[134:137], v[146:149], v[22:25]
	v_mfma_f32_16x16x32_bf16 v[110:113], v[122:125], v[142:145], v[110:113]
	v_mfma_f32_16x16x32_bf16 v[78:81], v[126:129], v[142:145], v[78:81]
	v_mfma_f32_16x16x32_bf16 v[46:49], v[130:133], v[142:145], v[46:49]
	v_mfma_f32_16x16x32_bf16 v[14:17], v[134:137], v[142:145], v[14:17]
	v_mfma_f32_16x16x32_bf16 v[102:105], v[122:125], v[138:141], v[102:105]
	v_mfma_f32_16x16x32_bf16 v[70:73], v[126:129], v[138:141], v[70:73]
	v_mfma_f32_16x16x32_bf16 v[38:41], v[130:133], v[138:141], v[38:41]
	v_mfma_f32_16x16x32_bf16 v[6:9], v[134:137], v[138:141], v[6:9]
	s_waitcnt vmcnt(0)
	s_waitcnt lgkmcnt(0)
	s_barrier
	v_mfma_f32_16x16x32_bf16 v[154:157], v[122:125], v[162:165], v[154:157]
	s_add_i32 s28, s31, 0xffff0000
	s_and_b32 s35, s28, 0x18000
	v_add_u32_e32 v187, s35, v200
	v_add_u32_e32 v226, s35, v201
	ds_read_b128 v[150:153], v226
	v_mfma_f32_16x16x32_bf16 v[90:93], v[126:129], v[162:165], v[90:93]
	ds_read_b128 v[146:149], v226 offset:1024
	v_mfma_f32_16x16x32_bf16 v[58:61], v[130:133], v[162:165], v[58:61]
	ds_read_b128 v[142:145], v226 offset:2048
	v_mfma_f32_16x16x32_bf16 v[26:29], v[134:137], v[162:165], v[26:29]
	ds_read_b128 v[138:141], v226 offset:3072
	v_mfma_f32_16x16x32_bf16 v[114:117], v[122:125], v[166:169], v[114:117]
	ds_read_b128 v[174:177], v187
	v_mfma_f32_16x16x32_bf16 v[82:85], v[126:129], v[166:169], v[82:85]
	ds_read_b128 v[170:173], v187 offset:1024
	v_mfma_f32_16x16x32_bf16 v[50:53], v[130:133], v[166:169], v[50:53]
	ds_read_b128 v[162:165], v187 offset:3072
	v_mfma_f32_16x16x32_bf16 v[18:21], v[134:137], v[166:169], v[18:21]
	ds_read_b128 v[166:169], v187 offset:2048
	v_mfma_f32_16x16x32_bf16 v[106:109], v[122:125], v[232:235], v[106:109]
	v_mfma_f32_16x16x32_bf16 v[74:77], v[126:129], v[232:235], v[74:77]
	v_mfma_f32_16x16x32_bf16 v[42:45], v[130:133], v[232:235], v[42:45]
	v_mfma_f32_16x16x32_bf16 v[10:13], v[134:137], v[232:235], v[10:13]
	v_mfma_f32_16x16x32_bf16 v[98:101], v[122:125], v[236:239], v[98:101]
	v_mfma_f32_16x16x32_bf16 v[66:69], v[126:129], v[236:239], v[66:69]
	v_mfma_f32_16x16x32_bf16 v[34:37], v[130:133], v[236:239], v[34:37]
	v_mfma_f32_16x16x32_bf16 v[2:5], v[134:137], v[236:239], v[2:5]
	s_waitcnt lgkmcnt(0)
	v_mfma_f32_16x16x32_bf16 v[158:161], v[174:177], v[150:153], v[158:161]
	v_mfma_f32_16x16x32_bf16 v[94:97], v[170:173], v[150:153], v[94:97]
	v_add_u32_e32 v226, s35, v230
	ds_read_b128 v[232:235], v226
	v_mfma_f32_16x16x32_bf16 v[62:65], v[166:169], v[150:153], v[62:65]
	ds_read_b128 v[236:239], v226 offset:1024
	v_mfma_f32_16x16x32_bf16 v[30:33], v[162:165], v[150:153], v[30:33]
	ds_read_b128 v[182:185], v226 offset:2048
	v_mfma_f32_16x16x32_bf16 v[118:121], v[174:177], v[146:149], v[118:121]
	ds_read_b128 v[178:181], v226 offset:3072
	v_mfma_f32_16x16x32_bf16 v[86:89], v[170:173], v[146:149], v[86:89]
	v_mfma_f32_16x16x32_bf16 v[54:57], v[166:169], v[146:149], v[54:57]
	v_mfma_f32_16x16x32_bf16 v[22:25], v[162:165], v[146:149], v[22:25]
	v_mfma_f32_16x16x32_bf16 v[110:113], v[174:177], v[142:145], v[110:113]
	v_mfma_f32_16x16x32_bf16 v[78:81], v[170:173], v[142:145], v[78:81]
	v_mfma_f32_16x16x32_bf16 v[46:49], v[166:169], v[142:145], v[46:49]
	v_mfma_f32_16x16x32_bf16 v[14:17], v[162:165], v[142:145], v[14:17]
	v_mfma_f32_16x16x32_bf16 v[102:105], v[174:177], v[138:141], v[102:105]
	v_mfma_f32_16x16x32_bf16 v[70:73], v[170:173], v[138:141], v[70:73]
	v_mfma_f32_16x16x32_bf16 v[38:41], v[166:169], v[138:141], v[38:41]
	v_mfma_f32_16x16x32_bf16 v[6:9], v[162:165], v[138:141], v[6:9]
	s_waitcnt vmcnt(0)
	s_waitcnt lgkmcnt(0)
	s_barrier
	v_mfma_f32_16x16x32_bf16 v[154:157], v[174:177], v[232:235], v[154:157]
	v_mfma_f32_16x16x32_bf16 v[90:93], v[170:173], v[232:235], v[90:93]
	v_mfma_f32_16x16x32_bf16 v[58:61], v[166:169], v[232:235], v[58:61]
	v_mfma_f32_16x16x32_bf16 v[26:29], v[162:165], v[232:235], v[26:29]
	v_mfma_f32_16x16x32_bf16 v[114:117], v[174:177], v[236:239], v[114:117]
	v_mfma_f32_16x16x32_bf16 v[82:85], v[170:173], v[236:239], v[82:85]
	v_mfma_f32_16x16x32_bf16 v[50:53], v[166:169], v[236:239], v[50:53]
	v_mfma_f32_16x16x32_bf16 v[18:21], v[162:165], v[236:239], v[18:21]
	s_add_i32 s19, s19, 2
	s_add_u32 s20, s20, 0x80
	s_addc_u32 s21, s21, 0
	s_add_i32 s31, s31, 0x10000
	v_mfma_f32_16x16x32_bf16 v[106:109], v[174:177], v[182:185], v[106:109]
	v_mfma_f32_16x16x32_bf16 v[74:77], v[170:173], v[182:185], v[74:77]
	v_mfma_f32_16x16x32_bf16 v[42:45], v[166:169], v[182:185], v[42:45]
	v_mfma_f32_16x16x32_bf16 v[10:13], v[162:165], v[182:185], v[10:13]
	v_mfma_f32_16x16x32_bf16 v[98:101], v[174:177], v[178:181], v[98:101]
	v_mfma_f32_16x16x32_bf16 v[66:69], v[170:173], v[178:181], v[66:69]
	v_mfma_f32_16x16x32_bf16 v[34:37], v[166:169], v[178:181], v[34:37]
	v_mfma_f32_16x16x32_bf16 v[2:5], v[162:165], v[178:181], v[2:5]
	s_branch .LBB0_197

.Lgf_G1x_top:
	s_waitcnt vmcnt(4)
	s_waitcnt lgkmcnt(0)
	s_barrier
	v_mfma_f32_16x16x32_bf16 v[126:129], v[130:133], v[158:161], v[126:129]
	v_mfma_f32_16x16x32_bf16 v[98:101], v[134:137], v[158:161], v[98:101]
	s_add_i32 s28, s31, 0xfffe8000
	s_and_b32 s34, s28, 0x10000
	v_add_u32_e32 v170, s34, v233
	ds_read_b128 v[162:165], v170
	v_mfma_f32_16x16x32_bf16 v[66:69], v[138:141], v[158:161], v[66:69]
	ds_read_b128 v[166:169], v170 offset:1024
	v_mfma_f32_16x16x32_bf16 v[34:37], v[142:145], v[158:161], v[34:37]
	ds_read_b128 v[234:237], v170 offset:2048
	v_mfma_f32_16x16x32_bf16 v[122:125], v[130:133], v[154:157], v[122:125]
	ds_read_b128 v[238:241], v170 offset:3072
	s_and_b32 s40, s31, 0x18000
	s_add_i32 s40, s40, s69
	s_mov_b32 m0, s40
	v_mfma_f32_16x16x32_bf16 v[90:93], v[134:137], v[154:157], v[90:93]
	v_mfma_f32_16x16x32_bf16 v[58:61], v[138:141], v[154:157], v[58:61]
	v_mfma_f32_16x16x32_bf16 v[26:29], v[142:145], v[154:157], v[26:29]
	global_load_lds_dwordx4 v188, s[94:95]
	s_add_i32 m0, s40, 0x2000
	v_mfma_f32_16x16x32_bf16 v[118:121], v[130:133], v[150:153], v[118:121]
	v_mfma_f32_16x16x32_bf16 v[86:89], v[134:137], v[150:153], v[86:89]
	v_mfma_f32_16x16x32_bf16 v[54:57], v[138:141], v[150:153], v[54:57]
	global_load_lds_dwordx4 v190, s[94:95]
	s_add_i32 m0, s40, 0x4000
	v_mfma_f32_16x16x32_bf16 v[22:25], v[142:145], v[150:153], v[22:25]
	v_mfma_f32_16x16x32_bf16 v[114:117], v[130:133], v[146:149], v[114:117]
	global_load_lds_dwordx4 v192, s[42:43]
	s_add_i32 m0, s40, 0x6000
	v_mfma_f32_16x16x32_bf16 v[82:85], v[134:137], v[146:149], v[82:85]
	global_load_lds_dwordx4 v194, s[42:43]
	s_add_u32 s94, s94, 64
	s_addc_u32 s95, s95, 0
	s_add_u32 s42, s42, 64
	s_addc_u32 s43, s43, 0
	v_mfma_f32_16x16x32_bf16 v[50:53], v[138:141], v[146:149], v[50:53]
	v_mfma_f32_16x16x32_bf16 v[18:21], v[142:145], v[146:149], v[18:21]
	s_waitcnt lgkmcnt(0)
	v_mfma_f32_16x16x32_bf16 v[110:113], v[130:133], v[162:165], v[110:113]
	s_add_i32 s28, s31, 0xffff0000
	s_and_b32 s35, s28, 0x18000
	v_add_u32_e32 v189, s35, v231
	v_add_u32_e32 v226, s35, v232
	ds_read_b128 v[158:161], v226
	v_mfma_f32_16x16x32_bf16 v[78:81], v[134:137], v[162:165], v[78:81]
	ds_read_b128 v[154:157], v226 offset:1024
	v_mfma_f32_16x16x32_bf16 v[46:49], v[138:141], v[162:165], v[46:49]
	ds_read_b128 v[150:153], v226 offset:2048
	v_mfma_f32_16x16x32_bf16 v[14:17], v[142:145], v[162:165], v[14:17]
	ds_read_b128 v[146:149], v226 offset:3072
	v_mfma_f32_16x16x32_bf16 v[106:109], v[130:133], v[166:169], v[106:109]
	ds_read_b128 v[174:177], v189
	v_mfma_f32_16x16x32_bf16 v[74:77], v[134:137], v[166:169], v[74:77]
	ds_read_b128 v[170:173], v189 offset:1024
	v_mfma_f32_16x16x32_bf16 v[42:45], v[138:141], v[166:169], v[42:45]
	ds_read_b128 v[162:165], v189 offset:3072
	v_mfma_f32_16x16x32_bf16 v[10:13], v[142:145], v[166:169], v[10:13]
	ds_read_b128 v[166:169], v189 offset:2048
	v_mfma_f32_16x16x32_bf16 v[102:105], v[130:133], v[234:237], v[102:105]
	v_mfma_f32_16x16x32_bf16 v[70:73], v[134:137], v[234:237], v[70:73]
	v_mfma_f32_16x16x32_bf16 v[38:41], v[138:141], v[234:237], v[38:41]
	v_mfma_f32_16x16x32_bf16 v[6:9], v[142:145], v[234:237], v[6:9]
	v_mfma_f32_16x16x32_bf16 v[94:97], v[130:133], v[238:241], v[94:97]
	v_mfma_f32_16x16x32_bf16 v[62:65], v[134:137], v[238:241], v[62:65]
	v_mfma_f32_16x16x32_bf16 v[30:33], v[138:141], v[238:241], v[30:33]
	v_mfma_f32_16x16x32_bf16 v[2:5], v[142:145], v[238:241], v[2:5]
	s_waitcnt vmcnt(4)
	s_waitcnt lgkmcnt(0)
	s_barrier
	v_mfma_f32_16x16x32_bf16 v[126:129], v[174:177], v[158:161], v[126:129]
	v_mfma_f32_16x16x32_bf16 v[98:101], v[170:173], v[158:161], v[98:101]
	v_add_u32_e32 v226, s35, v233
	ds_read_b128 v[234:237], v226
	v_mfma_f32_16x16x32_bf16 v[66:69], v[166:169], v[158:161], v[66:69]
	ds_read_b128 v[238:241], v226 offset:1024
	v_mfma_f32_16x16x32_bf16 v[34:37], v[162:165], v[158:161], v[34:37]
	ds_read_b128 v[182:185], v226 offset:2048
	v_mfma_f32_16x16x32_bf16 v[122:125], v[174:177], v[154:157], v[122:125]
	ds_read_b128 v[178:181], v226 offset:3072
	s_add_i32 s40, s34, s69
	s_mov_b32 m0, s40
	v_mfma_f32_16x16x32_bf16 v[90:93], v[170:173], v[154:157], v[90:93]
	v_mfma_f32_16x16x32_bf16 v[58:61], v[166:169], v[154:157], v[58:61]
	v_mfma_f32_16x16x32_bf16 v[26:29], v[162:165], v[154:157], v[26:29]
	global_load_lds_dwordx4 v188, s[94:95]
	s_add_i32 m0, s40, 0x2000
	v_mfma_f32_16x16x32_bf16 v[118:121], v[174:177], v[150:153], v[118:121]
	v_mfma_f32_16x16x32_bf16 v[86:89], v[170:173], v[150:153], v[86:89]
	v_mfma_f32_16x16x32_bf16 v[54:57], v[166:169], v[150:153], v[54:57]
	global_load_lds_dwordx4 v190, s[94:95]
	s_add_i32 m0, s40, 0x4000
	v_mfma_f32_16x16x32_bf16 v[22:25], v[162:165], v[150:153], v[22:25]
	v_mfma_f32_16x16x32_bf16 v[114:117], v[174:177], v[146:149], v[114:117]
	global_load_lds_dwordx4 v192, s[42:43]
	s_add_i32 m0, s40, 0x6000
	v_mfma_f32_16x16x32_bf16 v[82:85], v[170:173], v[146:149], v[82:85]
	global_load_lds_dwordx4 v194, s[42:43]
	s_add_u32 s94, s94, 64
	s_addc_u32 s95, s95, 0
	s_add_u32 s42, s42, 64
	s_addc_u32 s43, s43, 0
	v_mfma_f32_16x16x32_bf16 v[50:53], v[166:169], v[146:149], v[50:53]
	v_mfma_f32_16x16x32_bf16 v[18:21], v[162:165], v[146:149], v[18:21]
	s_waitcnt lgkmcnt(0)
	v_mfma_f32_16x16x32_bf16 v[110:113], v[174:177], v[234:237], v[110:113]
	s_add_i32 s24, s31, 0xffff8000
	s_and_b32 s24, s24, 0x10000
	v_add_u32_e32 v189, s24, v231
	v_add_u32_e32 v226, s24, v232
	ds_read_b128 v[158:161], v226
	v_mfma_f32_16x16x32_bf16 v[78:81], v[170:173], v[234:237], v[78:81]
	ds_read_b128 v[154:157], v226 offset:1024
	v_mfma_f32_16x16x32_bf16 v[46:49], v[166:169], v[234:237], v[46:49]
	ds_read_b128 v[150:153], v226 offset:2048
	v_mfma_f32_16x16x32_bf16 v[14:17], v[162:165], v[234:237], v[14:17]
	ds_read_b128 v[146:149], v226 offset:3072
	v_mfma_f32_16x16x32_bf16 v[106:109], v[174:177], v[238:241], v[106:109]
	ds_read_b128 v[130:133], v189
	v_mfma_f32_16x16x32_bf16 v[74:77], v[170:173], v[238:241], v[74:77]
	ds_read_b128 v[134:137], v189 offset:1024
	v_mfma_f32_16x16x32_bf16 v[42:45], v[166:169], v[238:241], v[42:45]
	ds_read_b128 v[138:141], v189 offset:2048
	v_mfma_f32_16x16x32_bf16 v[10:13], v[162:165], v[238:241], v[10:13]
	ds_read_b128 v[142:145], v189 offset:3072
	s_add_i32 s30, s30, 2
	s_add_u32 s20, s20, 0x80
	s_addc_u32 s21, s21, 0
	s_add_i32 s31, s31, 0x10000
	v_mfma_f32_16x16x32_bf16 v[102:105], v[174:177], v[182:185], v[102:105]
	v_mfma_f32_16x16x32_bf16 v[70:73], v[170:173], v[182:185], v[70:73]
	v_mfma_f32_16x16x32_bf16 v[38:41], v[166:169], v[182:185], v[38:41]
	v_mfma_f32_16x16x32_bf16 v[6:9], v[162:165], v[182:185], v[6:9]
	v_mfma_f32_16x16x32_bf16 v[94:97], v[174:177], v[178:181], v[94:97]
	v_mfma_f32_16x16x32_bf16 v[62:65], v[170:173], v[178:181], v[62:65]
	v_mfma_f32_16x16x32_bf16 v[30:33], v[166:169], v[178:181], v[30:33]
	v_mfma_f32_16x16x32_bf16 v[2:5], v[162:165], v[178:181], v[2:5]
	s_cmp_lt_u32 s30, 28
	s_cbranch_scc1 .Lgf_G1x_top
	s_waitcnt vmcnt(4)
	s_waitcnt lgkmcnt(0)
	s_barrier
	v_mfma_f32_16x16x32_bf16 v[126:129], v[130:133], v[158:161], v[126:129]
	v_mfma_f32_16x16x32_bf16 v[98:101], v[134:137], v[158:161], v[98:101]
	s_add_i32 s28, s31, 0xfffe8000
	s_and_b32 s34, s28, 0x10000
	v_add_u32_e32 v170, s34, v233
	ds_read_b128 v[162:165], v170
	v_mfma_f32_16x16x32_bf16 v[66:69], v[138:141], v[158:161], v[66:69]
	ds_read_b128 v[166:169], v170 offset:1024
	v_mfma_f32_16x16x32_bf16 v[34:37], v[142:145], v[158:161], v[34:37]
	ds_read_b128 v[234:237], v170 offset:2048
	v_mfma_f32_16x16x32_bf16 v[122:125], v[130:133], v[154:157], v[122:125]
	ds_read_b128 v[238:241], v170 offset:3072
	s_and_b32 s40, s31, 0x18000
	s_add_i32 s40, s40, s69
	s_mov_b32 m0, s40
	v_mfma_f32_16x16x32_bf16 v[90:93], v[134:137], v[154:157], v[90:93]
	v_mfma_f32_16x16x32_bf16 v[58:61], v[138:141], v[154:157], v[58:61]
	v_mfma_f32_16x16x32_bf16 v[26:29], v[142:145], v[154:157], v[26:29]
	global_load_lds_dwordx4 v188, s[94:95]
	s_add_i32 m0, s40, 0x2000
	v_mfma_f32_16x16x32_bf16 v[118:121], v[130:133], v[150:153], v[118:121]
	v_mfma_f32_16x16x32_bf16 v[86:89], v[134:137], v[150:153], v[86:89]
	v_mfma_f32_16x16x32_bf16 v[54:57], v[138:141], v[150:153], v[54:57]
	global_load_lds_dwordx4 v190, s[94:95]
	s_add_i32 m0, s40, 0x4000
	v_mfma_f32_16x16x32_bf16 v[22:25], v[142:145], v[150:153], v[22:25]
	v_mfma_f32_16x16x32_bf16 v[114:117], v[130:133], v[146:149], v[114:117]
	global_load_lds_dwordx4 v192, s[42:43]
	s_add_i32 m0, s40, 0x6000
	v_mfma_f32_16x16x32_bf16 v[82:85], v[134:137], v[146:149], v[82:85]
	global_load_lds_dwordx4 v194, s[42:43]
	s_add_u32 s94, s94, 64
	s_addc_u32 s95, s95, 0
	s_add_u32 s42, s42, 64
	s_addc_u32 s43, s43, 0
	v_mfma_f32_16x16x32_bf16 v[50:53], v[138:141], v[146:149], v[50:53]
	v_mfma_f32_16x16x32_bf16 v[18:21], v[142:145], v[146:149], v[18:21]
	s_waitcnt lgkmcnt(0)
	v_mfma_f32_16x16x32_bf16 v[110:113], v[130:133], v[162:165], v[110:113]
	s_add_i32 s28, s31, 0xffff0000
	s_and_b32 s35, s28, 0x18000
	v_add_u32_e32 v189, s35, v231
	v_add_u32_e32 v226, s35, v232
	ds_read_b128 v[158:161], v226
	v_mfma_f32_16x16x32_bf16 v[78:81], v[134:137], v[162:165], v[78:81]
	ds_read_b128 v[154:157], v226 offset:1024
	v_mfma_f32_16x16x32_bf16 v[46:49], v[138:141], v[162:165], v[46:49]
	ds_read_b128 v[150:153], v226 offset:2048
	v_mfma_f32_16x16x32_bf16 v[14:17], v[142:145], v[162:165], v[14:17]
	ds_read_b128 v[146:149], v226 offset:3072
	v_mfma_f32_16x16x32_bf16 v[106:109], v[130:133], v[166:169], v[106:109]
	ds_read_b128 v[174:177], v189
	v_mfma_f32_16x16x32_bf16 v[74:77], v[134:137], v[166:169], v[74:77]
	ds_read_b128 v[170:173], v189 offset:1024
	v_mfma_f32_16x16x32_bf16 v[42:45], v[138:141], v[166:169], v[42:45]
	ds_read_b128 v[162:165], v189 offset:3072
	v_mfma_f32_16x16x32_bf16 v[10:13], v[142:145], v[166:169], v[10:13]
	ds_read_b128 v[166:169], v189 offset:2048
	v_mfma_f32_16x16x32_bf16 v[102:105], v[130:133], v[234:237], v[102:105]
	v_mfma_f32_16x16x32_bf16 v[70:73], v[134:137], v[234:237], v[70:73]
	v_mfma_f32_16x16x32_bf16 v[38:41], v[138:141], v[234:237], v[38:41]
	v_mfma_f32_16x16x32_bf16 v[6:9], v[142:145], v[234:237], v[6:9]
	v_mfma_f32_16x16x32_bf16 v[94:97], v[130:133], v[238:241], v[94:97]
	v_mfma_f32_16x16x32_bf16 v[62:65], v[134:137], v[238:241], v[62:65]
	v_mfma_f32_16x16x32_bf16 v[30:33], v[138:141], v[238:241], v[30:33]
	v_mfma_f32_16x16x32_bf16 v[2:5], v[142:145], v[238:241], v[2:5]
	s_waitcnt vmcnt(4)
	s_waitcnt lgkmcnt(0)
	s_barrier
	v_mfma_f32_16x16x32_bf16 v[126:129], v[174:177], v[158:161], v[126:129]
	v_mfma_f32_16x16x32_bf16 v[98:101], v[170:173], v[158:161], v[98:101]
	v_add_u32_e32 v226, s35, v233
	ds_read_b128 v[234:237], v226
	v_mfma_f32_16x16x32_bf16 v[66:69], v[166:169], v[158:161], v[66:69]
	ds_read_b128 v[238:241], v226 offset:1024
	v_mfma_f32_16x16x32_bf16 v[34:37], v[162:165], v[158:161], v[34:37]
	ds_read_b128 v[182:185], v226 offset:2048
	v_mfma_f32_16x16x32_bf16 v[122:125], v[174:177], v[154:157], v[122:125]
	ds_read_b128 v[178:181], v226 offset:3072
	v_mfma_f32_16x16x32_bf16 v[90:93], v[170:173], v[154:157], v[90:93]
	v_mfma_f32_16x16x32_bf16 v[58:61], v[166:169], v[154:157], v[58:61]
	v_mfma_f32_16x16x32_bf16 v[26:29], v[162:165], v[154:157], v[26:29]
	v_mfma_f32_16x16x32_bf16 v[118:121], v[174:177], v[150:153], v[118:121]
	v_mfma_f32_16x16x32_bf16 v[86:89], v[170:173], v[150:153], v[86:89]
	v_mfma_f32_16x16x32_bf16 v[54:57], v[166:169], v[150:153], v[54:57]
	v_mfma_f32_16x16x32_bf16 v[22:25], v[162:165], v[150:153], v[22:25]
	v_mfma_f32_16x16x32_bf16 v[114:117], v[174:177], v[146:149], v[114:117]
	v_mfma_f32_16x16x32_bf16 v[82:85], v[170:173], v[146:149], v[82:85]
	v_mfma_f32_16x16x32_bf16 v[50:53], v[166:169], v[146:149], v[50:53]
	v_mfma_f32_16x16x32_bf16 v[18:21], v[162:165], v[146:149], v[18:21]
	s_waitcnt lgkmcnt(0)
	v_mfma_f32_16x16x32_bf16 v[110:113], v[174:177], v[234:237], v[110:113]
	s_add_i32 s24, s31, 0xffff8000
	s_and_b32 s24, s24, 0x10000
	v_add_u32_e32 v189, s24, v231
	v_add_u32_e32 v226, s24, v232
	ds_read_b128 v[158:161], v226
	v_mfma_f32_16x16x32_bf16 v[78:81], v[170:173], v[234:237], v[78:81]
	ds_read_b128 v[154:157], v226 offset:1024
	v_mfma_f32_16x16x32_bf16 v[46:49], v[166:169], v[234:237], v[46:49]
	ds_read_b128 v[150:153], v226 offset:2048
	v_mfma_f32_16x16x32_bf16 v[14:17], v[162:165], v[234:237], v[14:17]
	ds_read_b128 v[146:149], v226 offset:3072
	v_mfma_f32_16x16x32_bf16 v[106:109], v[174:177], v[238:241], v[106:109]
	ds_read_b128 v[130:133], v189
	v_mfma_f32_16x16x32_bf16 v[74:77], v[170:173], v[238:241], v[74:77]
	ds_read_b128 v[134:137], v189 offset:1024
	v_mfma_f32_16x16x32_bf16 v[42:45], v[166:169], v[238:241], v[42:45]
	ds_read_b128 v[138:141], v189 offset:2048
	v_mfma_f32_16x16x32_bf16 v[10:13], v[162:165], v[238:241], v[10:13]
	ds_read_b128 v[142:145], v189 offset:3072
	s_add_i32 s30, s30, 2
	s_add_u32 s20, s20, 0x80
	s_addc_u32 s21, s21, 0
	s_add_i32 s31, s31, 0x10000
	v_mfma_f32_16x16x32_bf16 v[102:105], v[174:177], v[182:185], v[102:105]
	v_mfma_f32_16x16x32_bf16 v[70:73], v[170:173], v[182:185], v[70:73]
	v_mfma_f32_16x16x32_bf16 v[38:41], v[166:169], v[182:185], v[38:41]
	v_mfma_f32_16x16x32_bf16 v[6:9], v[162:165], v[182:185], v[6:9]
	v_mfma_f32_16x16x32_bf16 v[94:97], v[174:177], v[178:181], v[94:97]
	v_mfma_f32_16x16x32_bf16 v[62:65], v[170:173], v[178:181], v[62:65]
	v_mfma_f32_16x16x32_bf16 v[30:33], v[166:169], v[178:181], v[30:33]
	v_mfma_f32_16x16x32_bf16 v[2:5], v[162:165], v[178:181], v[2:5]
	s_waitcnt vmcnt(0)
	s_waitcnt lgkmcnt(0)
	s_barrier
	v_mfma_f32_16x16x32_bf16 v[126:129], v[130:133], v[158:161], v[126:129]
	v_mfma_f32_16x16x32_bf16 v[98:101], v[134:137], v[158:161], v[98:101]
	s_add_i32 s28, s31, 0xfffe8000
	s_and_b32 s34, s28, 0x10000
	v_add_u32_e32 v170, s34, v233
	ds_read_b128 v[162:165], v170
	v_mfma_f32_16x16x32_bf16 v[66:69], v[138:141], v[158:161], v[66:69]
	ds_read_b128 v[166:169], v170 offset:1024
	v_mfma_f32_16x16x32_bf16 v[34:37], v[142:145], v[158:161], v[34:37]
	ds_read_b128 v[234:237], v170 offset:2048
	v_mfma_f32_16x16x32_bf16 v[122:125], v[130:133], v[154:157], v[122:125]
	ds_read_b128 v[238:241], v170 offset:3072
	v_mfma_f32_16x16x32_bf16 v[90:93], v[134:137], v[154:157], v[90:93]
	v_mfma_f32_16x16x32_bf16 v[58:61], v[138:141], v[154:157], v[58:61]
	v_mfma_f32_16x16x32_bf16 v[26:29], v[142:145], v[154:157], v[26:29]
	v_mfma_f32_16x16x32_bf16 v[118:121], v[130:133], v[150:153], v[118:121]
	v_mfma_f32_16x16x32_bf16 v[86:89], v[134:137], v[150:153], v[86:89]
	v_mfma_f32_16x16x32_bf16 v[54:57], v[138:141], v[150:153], v[54:57]
	v_mfma_f32_16x16x32_bf16 v[22:25], v[142:145], v[150:153], v[22:25]
	v_mfma_f32_16x16x32_bf16 v[114:117], v[130:133], v[146:149], v[114:117]
	v_mfma_f32_16x16x32_bf16 v[82:85], v[134:137], v[146:149], v[82:85]
	v_mfma_f32_16x16x32_bf16 v[50:53], v[138:141], v[146:149], v[50:53]
	v_mfma_f32_16x16x32_bf16 v[18:21], v[142:145], v[146:149], v[18:21]
	s_waitcnt lgkmcnt(0)
	v_mfma_f32_16x16x32_bf16 v[110:113], v[130:133], v[162:165], v[110:113]
	s_add_i32 s28, s31, 0xffff0000
	s_and_b32 s35, s28, 0x18000
	v_add_u32_e32 v189, s35, v231
	v_add_u32_e32 v226, s35, v232
	ds_read_b128 v[158:161], v226
	v_mfma_f32_16x16x32_bf16 v[78:81], v[134:137], v[162:165], v[78:81]
	ds_read_b128 v[154:157], v226 offset:1024
	v_mfma_f32_16x16x32_bf16 v[46:49], v[138:141], v[162:165], v[46:49]
	ds_read_b128 v[150:153], v226 offset:2048
	v_mfma_f32_16x16x32_bf16 v[14:17], v[142:145], v[162:165], v[14:17]
	ds_read_b128 v[146:149], v226 offset:3072
	v_mfma_f32_16x16x32_bf16 v[106:109], v[130:133], v[166:169], v[106:109]
	ds_read_b128 v[174:177], v189
	v_mfma_f32_16x16x32_bf16 v[74:77], v[134:137], v[166:169], v[74:77]
	ds_read_b128 v[170:173], v189 offset:1024
	v_mfma_f32_16x16x32_bf16 v[42:45], v[138:141], v[166:169], v[42:45]
	ds_read_b128 v[162:165], v189 offset:3072
	v_mfma_f32_16x16x32_bf16 v[10:13], v[142:145], v[166:169], v[10:13]
	ds_read_b128 v[166:169], v189 offset:2048
	v_mfma_f32_16x16x32_bf16 v[102:105], v[130:133], v[234:237], v[102:105]
	v_mfma_f32_16x16x32_bf16 v[70:73], v[134:137], v[234:237], v[70:73]
	v_mfma_f32_16x16x32_bf16 v[38:41], v[138:141], v[234:237], v[38:41]
	v_mfma_f32_16x16x32_bf16 v[6:9], v[142:145], v[234:237], v[6:9]
	v_mfma_f32_16x16x32_bf16 v[94:97], v[130:133], v[238:241], v[94:97]
	v_mfma_f32_16x16x32_bf16 v[62:65], v[134:137], v[238:241], v[62:65]
	v_mfma_f32_16x16x32_bf16 v[30:33], v[138:141], v[238:241], v[30:33]
	v_mfma_f32_16x16x32_bf16 v[2:5], v[142:145], v[238:241], v[2:5]
	s_waitcnt vmcnt(0)
	s_waitcnt lgkmcnt(0)
	s_barrier
	v_mfma_f32_16x16x32_bf16 v[126:129], v[174:177], v[158:161], v[126:129]
	v_mfma_f32_16x16x32_bf16 v[98:101], v[170:173], v[158:161], v[98:101]
	v_add_u32_e32 v226, s35, v233
	ds_read_b128 v[234:237], v226
	v_mfma_f32_16x16x32_bf16 v[66:69], v[166:169], v[158:161], v[66:69]
	ds_read_b128 v[238:241], v226 offset:1024
	v_mfma_f32_16x16x32_bf16 v[34:37], v[162:165], v[158:161], v[34:37]
	ds_read_b128 v[182:185], v226 offset:2048
	v_mfma_f32_16x16x32_bf16 v[122:125], v[174:177], v[154:157], v[122:125]
	ds_read_b128 v[178:181], v226 offset:3072
	v_mfma_f32_16x16x32_bf16 v[90:93], v[170:173], v[154:157], v[90:93]
	v_mfma_f32_16x16x32_bf16 v[58:61], v[166:169], v[154:157], v[58:61]
	v_mfma_f32_16x16x32_bf16 v[26:29], v[162:165], v[154:157], v[26:29]
	v_mfma_f32_16x16x32_bf16 v[118:121], v[174:177], v[150:153], v[118:121]
	v_mfma_f32_16x16x32_bf16 v[86:89], v[170:173], v[150:153], v[86:89]
	v_mfma_f32_16x16x32_bf16 v[54:57], v[166:169], v[150:153], v[54:57]
	v_mfma_f32_16x16x32_bf16 v[22:25], v[162:165], v[150:153], v[22:25]
	v_mfma_f32_16x16x32_bf16 v[114:117], v[174:177], v[146:149], v[114:117]
	v_mfma_f32_16x16x32_bf16 v[82:85], v[170:173], v[146:149], v[82:85]
	v_mfma_f32_16x16x32_bf16 v[50:53], v[166:169], v[146:149], v[50:53]
	v_mfma_f32_16x16x32_bf16 v[18:21], v[162:165], v[146:149], v[18:21]
	s_waitcnt lgkmcnt(0)
	v_mfma_f32_16x16x32_bf16 v[110:113], v[174:177], v[234:237], v[110:113]
	v_mfma_f32_16x16x32_bf16 v[78:81], v[170:173], v[234:237], v[78:81]
	v_mfma_f32_16x16x32_bf16 v[46:49], v[166:169], v[234:237], v[46:49]
	v_mfma_f32_16x16x32_bf16 v[14:17], v[162:165], v[234:237], v[14:17]
	v_mfma_f32_16x16x32_bf16 v[106:109], v[174:177], v[238:241], v[106:109]
	v_mfma_f32_16x16x32_bf16 v[74:77], v[170:173], v[238:241], v[74:77]
	v_mfma_f32_16x16x32_bf16 v[42:45], v[166:169], v[238:241], v[42:45]
	v_mfma_f32_16x16x32_bf16 v[10:13], v[162:165], v[238:241], v[10:13]
	s_add_i32 s30, s30, 2
	s_add_u32 s20, s20, 0x80
	s_addc_u32 s21, s21, 0
	s_add_i32 s31, s31, 0x10000
	v_mfma_f32_16x16x32_bf16 v[102:105], v[174:177], v[182:185], v[102:105]
	v_mfma_f32_16x16x32_bf16 v[70:73], v[170:173], v[182:185], v[70:73]
	v_mfma_f32_16x16x32_bf16 v[38:41], v[166:169], v[182:185], v[38:41]
	v_mfma_f32_16x16x32_bf16 v[6:9], v[162:165], v[182:185], v[6:9]
	v_mfma_f32_16x16x32_bf16 v[94:97], v[174:177], v[178:181], v[94:97]
	v_mfma_f32_16x16x32_bf16 v[62:65], v[170:173], v[178:181], v[62:65]
	v_mfma_f32_16x16x32_bf16 v[30:33], v[166:169], v[178:181], v[30:33]
	v_mfma_f32_16x16x32_bf16 v[2:5], v[162:165], v[178:181], v[2:5]
	s_branch .LBB0_659
.Lgr_G1x_entry:
	s_waitcnt vmcnt(4)
	s_waitcnt lgkmcnt(0)
	s_barrier
	v_mfma_f32_16x16x32_bf16 v[126:129], v[130:133], v[158:161], v[126:129]
	v_mfma_f32_16x16x32_bf16 v[98:101], v[134:137], v[158:161], v[98:101]
	s_add_i32 s28, s31, 0xfffe8000
	s_and_b32 s34, s28, 0x10000
	v_add_u32_e32 v170, s34, v233
	ds_read_b128 v[162:165], v170
	v_mfma_f32_16x16x32_bf16 v[66:69], v[138:141], v[158:161], v[66:69]
	ds_read_b128 v[166:169], v170 offset:1024
	v_mfma_f32_16x16x32_bf16 v[34:37], v[142:145], v[158:161], v[34:37]
	ds_read_b128 v[234:237], v170 offset:2048
	v_mfma_f32_16x16x32_bf16 v[122:125], v[130:133], v[154:157], v[122:125]
	ds_read_b128 v[238:241], v170 offset:3072
	s_and_b32 s40, s31, 0x18000
	s_add_i32 s40, s40, s69
	s_mov_b32 m0, s40
	v_mfma_f32_16x16x32_bf16 v[90:93], v[134:137], v[154:157], v[90:93]
	v_mfma_f32_16x16x32_bf16 v[58:61], v[138:141], v[154:157], v[58:61]
	v_mfma_f32_16x16x32_bf16 v[26:29], v[142:145], v[154:157], v[26:29]
	global_load_lds_dwordx4 v188, s[94:95]
	s_add_i32 m0, s40, 0x2000
	v_mfma_f32_16x16x32_bf16 v[118:121], v[130:133], v[150:153], v[118:121]
	v_mfma_f32_16x16x32_bf16 v[86:89], v[134:137], v[150:153], v[86:89]
	v_mfma_f32_16x16x32_bf16 v[54:57], v[138:141], v[150:153], v[54:57]
	global_load_lds_dwordx4 v190, s[94:95]
	s_add_i32 m0, s40, 0x4000
	v_mfma_f32_16x16x32_bf16 v[22:25], v[142:145], v[150:153], v[22:25]
	v_mfma_f32_16x16x32_bf16 v[114:117], v[130:133], v[146:149], v[114:117]
	global_load_lds_dwordx4 v192, s[42:43]
	s_add_i32 m0, s40, 0x6000
	v_mfma_f32_16x16x32_bf16 v[82:85], v[134:137], v[146:149], v[82:85]
	global_load_lds_dwordx4 v194, s[42:43]
	s_add_u32 s94, s94, 64
	s_addc_u32 s95, s95, 0
	s_add_u32 s42, s42, 64
	s_addc_u32 s43, s43, 0
	v_mfma_f32_16x16x32_bf16 v[50:53], v[138:141], v[146:149], v[50:53]
	v_mfma_f32_16x16x32_bf16 v[18:21], v[142:145], v[146:149], v[18:21]
	s_waitcnt vmcnt(4)
	s_waitcnt lgkmcnt(0)
	s_barrier
	v_mfma_f32_16x16x32_bf16 v[110:113], v[130:133], v[162:165], v[110:113]
	s_add_i32 s28, s31, 0xffff0000
	s_and_b32 s35, s28, 0x18000
	v_add_u32_e32 v189, s35, v231
	v_add_u32_e32 v226, s35, v232
	ds_read_b128 v[158:161], v226
	v_mfma_f32_16x16x32_bf16 v[78:81], v[134:137], v[162:165], v[78:81]
	ds_read_b128 v[154:157], v226 offset:1024
	v_mfma_f32_16x16x32_bf16 v[46:49], v[138:141], v[162:165], v[46:49]
	ds_read_b128 v[150:153], v226 offset:2048
	v_mfma_f32_16x16x32_bf16 v[14:17], v[142:145], v[162:165], v[14:17]
	ds_read_b128 v[146:149], v226 offset:3072
	v_mfma_f32_16x16x32_bf16 v[106:109], v[130:133], v[166:169], v[106:109]
	ds_read_b128 v[174:177], v189
	v_mfma_f32_16x16x32_bf16 v[74:77], v[134:137], v[166:169], v[74:77]
	ds_read_b128 v[170:173], v189 offset:1024
	v_mfma_f32_16x16x32_bf16 v[42:45], v[138:141], v[166:169], v[42:45]
	ds_read_b128 v[162:165], v189 offset:3072
	v_mfma_f32_16x16x32_bf16 v[10:13], v[142:145], v[166:169], v[10:13]
	ds_read_b128 v[166:169], v189 offset:2048
	v_mfma_f32_16x16x32_bf16 v[102:105], v[130:133], v[234:237], v[102:105]
	v_mfma_f32_16x16x32_bf16 v[70:73], v[134:137], v[234:237], v[70:73]
	v_mfma_f32_16x16x32_bf16 v[38:41], v[138:141], v[234:237], v[38:41]
	v_mfma_f32_16x16x32_bf16 v[6:9], v[142:145], v[234:237], v[6:9]
	v_mfma_f32_16x16x32_bf16 v[94:97], v[130:133], v[238:241], v[94:97]
	v_mfma_f32_16x16x32_bf16 v[62:65], v[134:137], v[238:241], v[62:65]
	v_mfma_f32_16x16x32_bf16 v[30:33], v[138:141], v[238:241], v[30:33]
	v_mfma_f32_16x16x32_bf16 v[2:5], v[142:145], v[238:241], v[2:5]
	s_waitcnt lgkmcnt(0)
	v_mfma_f32_16x16x32_bf16 v[126:129], v[174:177], v[158:161], v[126:129]
	v_mfma_f32_16x16x32_bf16 v[98:101], v[170:173], v[158:161], v[98:101]
	v_add_u32_e32 v226, s35, v233
	ds_read_b128 v[234:237], v226
	v_mfma_f32_16x16x32_bf16 v[66:69], v[166:169], v[158:161], v[66:69]
	ds_read_b128 v[238:241], v226 offset:1024
	v_mfma_f32_16x16x32_bf16 v[34:37], v[162:165], v[158:161], v[34:37]
	ds_read_b128 v[182:185], v226 offset:2048
	v_mfma_f32_16x16x32_bf16 v[122:125], v[174:177], v[154:157], v[122:125]
	ds_read_b128 v[178:181], v226 offset:3072
	s_add_i32 s40, s34, s69
	s_mov_b32 m0, s40
	v_mfma_f32_16x16x32_bf16 v[90:93], v[170:173], v[154:157], v[90:93]
	v_mfma_f32_16x16x32_bf16 v[58:61], v[166:169], v[154:157], v[58:61]
	v_mfma_f32_16x16x32_bf16 v[26:29], v[162:165], v[154:157], v[26:29]
	global_load_lds_dwordx4 v188, s[94:95]
	s_add_i32 m0, s40, 0x2000
	v_mfma_f32_16x16x32_bf16 v[118:121], v[174:177], v[150:153], v[118:121]
	v_mfma_f32_16x16x32_bf16 v[86:89], v[170:173], v[150:153], v[86:89]
	v_mfma_f32_16x16x32_bf16 v[54:57], v[166:169], v[150:153], v[54:57]
	global_load_lds_dwordx4 v190, s[94:95]
	s_add_i32 m0, s40, 0x4000
	v_mfma_f32_16x16x32_bf16 v[22:25], v[162:165], v[150:153], v[22:25]
	v_mfma_f32_16x16x32_bf16 v[114:117], v[174:177], v[146:149], v[114:117]
	global_load_lds_dwordx4 v192, s[42:43]
	s_add_i32 m0, s40, 0x6000
	v_mfma_f32_16x16x32_bf16 v[82:85], v[170:173], v[146:149], v[82:85]
	global_load_lds_dwordx4 v194, s[42:43]
	s_add_u32 s94, s94, 64
	s_addc_u32 s95, s95, 0
	s_add_u32 s42, s42, 64
	s_addc_u32 s43, s43, 0
	v_mfma_f32_16x16x32_bf16 v[50:53], v[166:169], v[146:149], v[50:53]
	v_mfma_f32_16x16x32_bf16 v[18:21], v[162:165], v[146:149], v[18:21]
.Lgr_G1x_top:
	s_waitcnt vmcnt(4)
	s_waitcnt lgkmcnt(0)
	s_barrier
	v_mfma_f32_16x16x32_bf16 v[110:113], v[174:177], v[234:237], v[110:113]
	s_add_i32 s24, s31, 0xffff8000
	s_and_b32 s24, s24, 0x10000
	v_add_u32_e32 v189, s24, v231
	v_add_u32_e32 v226, s24, v232
	ds_read_b128 v[158:161], v226
	v_mfma_f32_16x16x32_bf16 v[78:81], v[170:173], v[234:237], v[78:81]
	ds_read_b128 v[154:157], v226 offset:1024
	v_mfma_f32_16x16x32_bf16 v[46:49], v[166:169], v[234:237], v[46:49]
	ds_read_b128 v[150:153], v226 offset:2048
	v_mfma_f32_16x16x32_bf16 v[14:17], v[162:165], v[234:237], v[14:17]
	ds_read_b128 v[146:149], v226 offset:3072
	v_mfma_f32_16x16x32_bf16 v[106:109], v[174:177], v[238:241], v[106:109]
	ds_read_b128 v[130:133], v189
	v_mfma_f32_16x16x32_bf16 v[74:77], v[170:173], v[238:241], v[74:77]
	ds_read_b128 v[134:137], v189 offset:1024
	v_mfma_f32_16x16x32_bf16 v[42:45], v[166:169], v[238:241], v[42:45]
	ds_read_b128 v[138:141], v189 offset:2048
	v_mfma_f32_16x16x32_bf16 v[10:13], v[162:165], v[238:241], v[10:13]
	ds_read_b128 v[142:145], v189 offset:3072
	s_add_i32 s30, s30, 2
	s_add_u32 s20, s20, 0x80
	s_addc_u32 s21, s21, 0
	s_add_i32 s31, s31, 0x10000
	v_mfma_f32_16x16x32_bf16 v[102:105], v[174:177], v[182:185], v[102:105]
	v_mfma_f32_16x16x32_bf16 v[70:73], v[170:173], v[182:185], v[70:73]
	v_mfma_f32_16x16x32_bf16 v[38:41], v[166:169], v[182:185], v[38:41]
	v_mfma_f32_16x16x32_bf16 v[6:9], v[162:165], v[182:185], v[6:9]
	v_mfma_f32_16x16x32_bf16 v[94:97], v[174:177], v[178:181], v[94:97]
	v_mfma_f32_16x16x32_bf16 v[62:65], v[170:173], v[178:181], v[62:65]
	v_mfma_f32_16x16x32_bf16 v[30:33], v[166:169], v[178:181], v[30:33]
	v_mfma_f32_16x16x32_bf16 v[2:5], v[162:165], v[178:181], v[2:5]
	s_cmp_lt_u32 s30, 28
	s_cbranch_scc0 .Lgr_G1x_tail
	s_waitcnt lgkmcnt(0)
	v_mfma_f32_16x16x32_bf16 v[126:129], v[130:133], v[158:161], v[126:129]
	v_mfma_f32_16x16x32_bf16 v[98:101], v[134:137], v[158:161], v[98:101]
	s_add_i32 s28, s31, 0xfffe8000
	s_and_b32 s34, s28, 0x10000
	v_add_u32_e32 v170, s34, v233
	ds_read_b128 v[162:165], v170
	v_mfma_f32_16x16x32_bf16 v[66:69], v[138:141], v[158:161], v[66:69]
	ds_read_b128 v[166:169], v170 offset:1024
	v_mfma_f32_16x16x32_bf16 v[34:37], v[142:145], v[158:161], v[34:37]
	ds_read_b128 v[234:237], v170 offset:2048
	v_mfma_f32_16x16x32_bf16 v[122:125], v[130:133], v[154:157], v[122:125]
	ds_read_b128 v[238:241], v170 offset:3072
	s_and_b32 s40, s31, 0x18000
	s_add_i32 s40, s40, s69
	s_mov_b32 m0, s40
	v_mfma_f32_16x16x32_bf16 v[90:93], v[134:137], v[154:157], v[90:93]
	v_mfma_f32_16x16x32_bf16 v[58:61], v[138:141], v[154:157], v[58:61]
	v_mfma_f32_16x16x32_bf16 v[26:29], v[142:145], v[154:157], v[26:29]
	global_load_lds_dwordx4 v188, s[94:95]
	s_add_i32 m0, s40, 0x2000
	v_mfma_f32_16x16x32_bf16 v[118:121], v[130:133], v[150:153], v[118:121]
	v_mfma_f32_16x16x32_bf16 v[86:89], v[134:137], v[150:153], v[86:89]
	v_mfma_f32_16x16x32_bf16 v[54:57], v[138:141], v[150:153], v[54:57]
	global_load_lds_dwordx4 v190, s[94:95]
	s_add_i32 m0, s40, 0x4000
	v_mfma_f32_16x16x32_bf16 v[22:25], v[142:145], v[150:153], v[22:25]
	v_mfma_f32_16x16x32_bf16 v[114:117], v[130:133], v[146:149], v[114:117]
	global_load_lds_dwordx4 v192, s[42:43]
	s_add_i32 m0, s40, 0x6000
	v_mfma_f32_16x16x32_bf16 v[82:85], v[134:137], v[146:149], v[82:85]
	global_load_lds_dwordx4 v194, s[42:43]
	s_add_u32 s94, s94, 64
	s_addc_u32 s95, s95, 0
	s_add_u32 s42, s42, 64
	s_addc_u32 s43, s43, 0
	v_mfma_f32_16x16x32_bf16 v[50:53], v[138:141], v[146:149], v[50:53]
	v_mfma_f32_16x16x32_bf16 v[18:21], v[142:145], v[146:149], v[18:21]
	s_waitcnt vmcnt(4)
	s_waitcnt lgkmcnt(0)
	s_barrier
	v_mfma_f32_16x16x32_bf16 v[110:113], v[130:133], v[162:165], v[110:113]
	s_add_i32 s28, s31, 0xffff0000
	s_and_b32 s35, s28, 0x18000
	v_add_u32_e32 v189, s35, v231
	v_add_u32_e32 v226, s35, v232
	ds_read_b128 v[158:161], v226
	v_mfma_f32_16x16x32_bf16 v[78:81], v[134:137], v[162:165], v[78:81]
	ds_read_b128 v[154:157], v226 offset:1024
	v_mfma_f32_16x16x32_bf16 v[46:49], v[138:141], v[162:165], v[46:49]
	ds_read_b128 v[150:153], v226 offset:2048
	v_mfma_f32_16x16x32_bf16 v[14:17], v[142:145], v[162:165], v[14:17]
	ds_read_b128 v[146:149], v226 offset:3072
	v_mfma_f32_16x16x32_bf16 v[106:109], v[130:133], v[166:169], v[106:109]
	ds_read_b128 v[174:177], v189
	v_mfma_f32_16x16x32_bf16 v[74:77], v[134:137], v[166:169], v[74:77]
	ds_read_b128 v[170:173], v189 offset:1024
	v_mfma_f32_16x16x32_bf16 v[42:45], v[138:141], v[166:169], v[42:45]
	ds_read_b128 v[162:165], v189 offset:3072
	v_mfma_f32_16x16x32_bf16 v[10:13], v[142:145], v[166:169], v[10:13]
	ds_read_b128 v[166:169], v189 offset:2048
	v_mfma_f32_16x16x32_bf16 v[102:105], v[130:133], v[234:237], v[102:105]
	v_mfma_f32_16x16x32_bf16 v[70:73], v[134:137], v[234:237], v[70:73]
	v_mfma_f32_16x16x32_bf16 v[38:41], v[138:141], v[234:237], v[38:41]
	v_mfma_f32_16x16x32_bf16 v[6:9], v[142:145], v[234:237], v[6:9]
	v_mfma_f32_16x16x32_bf16 v[94:97], v[130:133], v[238:241], v[94:97]
	v_mfma_f32_16x16x32_bf16 v[62:65], v[134:137], v[238:241], v[62:65]
	v_mfma_f32_16x16x32_bf16 v[30:33], v[138:141], v[238:241], v[30:33]
	v_mfma_f32_16x16x32_bf16 v[2:5], v[142:145], v[238:241], v[2:5]
	s_waitcnt lgkmcnt(0)
	v_mfma_f32_16x16x32_bf16 v[126:129], v[174:177], v[158:161], v[126:129]
	v_mfma_f32_16x16x32_bf16 v[98:101], v[170:173], v[158:161], v[98:101]
	v_add_u32_e32 v226, s35, v233
	ds_read_b128 v[234:237], v226
	v_mfma_f32_16x16x32_bf16 v[66:69], v[166:169], v[158:161], v[66:69]
	ds_read_b128 v[238:241], v226 offset:1024
	v_mfma_f32_16x16x32_bf16 v[34:37], v[162:165], v[158:161], v[34:37]
	ds_read_b128 v[182:185], v226 offset:2048
	v_mfma_f32_16x16x32_bf16 v[122:125], v[174:177], v[154:157], v[122:125]
	ds_read_b128 v[178:181], v226 offset:3072
	s_add_i32 s40, s34, s69
	s_mov_b32 m0, s40
	v_mfma_f32_16x16x32_bf16 v[90:93], v[170:173], v[154:157], v[90:93]
	v_mfma_f32_16x16x32_bf16 v[58:61], v[166:169], v[154:157], v[58:61]
	v_mfma_f32_16x16x32_bf16 v[26:29], v[162:165], v[154:157], v[26:29]
	global_load_lds_dwordx4 v188, s[94:95]
	s_add_i32 m0, s40, 0x2000
	v_mfma_f32_16x16x32_bf16 v[118:121], v[174:177], v[150:153], v[118:121]
	v_mfma_f32_16x16x32_bf16 v[86:89], v[170:173], v[150:153], v[86:89]
	v_mfma_f32_16x16x32_bf16 v[54:57], v[166:169], v[150:153], v[54:57]
	global_load_lds_dwordx4 v190, s[94:95]
	s_add_i32 m0, s40, 0x4000
	v_mfma_f32_16x16x32_bf16 v[22:25], v[162:165], v[150:153], v[22:25]
	v_mfma_f32_16x16x32_bf16 v[114:117], v[174:177], v[146:149], v[114:117]
	global_load_lds_dwordx4 v192, s[42:43]
	s_add_i32 m0, s40, 0x6000
	v_mfma_f32_16x16x32_bf16 v[82:85], v[170:173], v[146:149], v[82:85]
	global_load_lds_dwordx4 v194, s[42:43]
	s_add_u32 s94, s94, 64
	s_addc_u32 s95, s95, 0
	s_add_u32 s42, s42, 64
	s_addc_u32 s43, s43, 0
	v_mfma_f32_16x16x32_bf16 v[50:53], v[166:169], v[146:149], v[50:53]
	v_mfma_f32_16x16x32_bf16 v[18:21], v[162:165], v[146:149], v[18:21]
	s_branch .Lgr_G1x_top
.Lgr_G1x_tail:
	s_waitcnt lgkmcnt(0)
	v_mfma_f32_16x16x32_bf16 v[126:129], v[130:133], v[158:161], v[126:129]
	v_mfma_f32_16x16x32_bf16 v[98:101], v[134:137], v[158:161], v[98:101]
	s_add_i32 s28, s31, 0xfffe8000
	s_and_b32 s34, s28, 0x10000
	v_add_u32_e32 v170, s34, v233
	ds_read_b128 v[162:165], v170
	v_mfma_f32_16x16x32_bf16 v[66:69], v[138:141], v[158:161], v[66:69]
	ds_read_b128 v[166:169], v170 offset:1024
	v_mfma_f32_16x16x32_bf16 v[34:37], v[142:145], v[158:161], v[34:37]
	ds_read_b128 v[234:237], v170 offset:2048
	v_mfma_f32_16x16x32_bf16 v[122:125], v[130:133], v[154:157], v[122:125]
	ds_read_b128 v[238:241], v170 offset:3072
	s_and_b32 s40, s31, 0x18000
	s_add_i32 s40, s40, s69
	s_mov_b32 m0, s40
	v_mfma_f32_16x16x32_bf16 v[90:93], v[134:137], v[154:157], v[90:93]
	v_mfma_f32_16x16x32_bf16 v[58:61], v[138:141], v[154:157], v[58:61]
	v_mfma_f32_16x16x32_bf16 v[26:29], v[142:145], v[154:157], v[26:29]
	global_load_lds_dwordx4 v188, s[94:95]
	s_add_i32 m0, s40, 0x2000
	v_mfma_f32_16x16x32_bf16 v[118:121], v[130:133], v[150:153], v[118:121]
	v_mfma_f32_16x16x32_bf16 v[86:89], v[134:137], v[150:153], v[86:89]
	v_mfma_f32_16x16x32_bf16 v[54:57], v[138:141], v[150:153], v[54:57]
	global_load_lds_dwordx4 v190, s[94:95]
	s_add_i32 m0, s40, 0x4000
	v_mfma_f32_16x16x32_bf16 v[22:25], v[142:145], v[150:153], v[22:25]
	v_mfma_f32_16x16x32_bf16 v[114:117], v[130:133], v[146:149], v[114:117]
	global_load_lds_dwordx4 v192, s[42:43]
	s_add_i32 m0, s40, 0x6000
	v_mfma_f32_16x16x32_bf16 v[82:85], v[134:137], v[146:149], v[82:85]
	global_load_lds_dwordx4 v194, s[42:43]
	s_add_u32 s94, s94, 64
	s_addc_u32 s95, s95, 0
	s_add_u32 s42, s42, 64
	s_addc_u32 s43, s43, 0
	v_mfma_f32_16x16x32_bf16 v[50:53], v[138:141], v[146:149], v[50:53]
	v_mfma_f32_16x16x32_bf16 v[18:21], v[142:145], v[146:149], v[18:21]
	s_waitcnt vmcnt(4)
	s_waitcnt lgkmcnt(0)
	s_barrier
	v_mfma_f32_16x16x32_bf16 v[110:113], v[130:133], v[162:165], v[110:113]
	s_add_i32 s28, s31, 0xffff0000
	s_and_b32 s35, s28, 0x18000
	v_add_u32_e32 v189, s35, v231
	v_add_u32_e32 v226, s35, v232
	ds_read_b128 v[158:161], v226
	v_mfma_f32_16x16x32_bf16 v[78:81], v[134:137], v[162:165], v[78:81]
	ds_read_b128 v[154:157], v226 offset:1024
	v_mfma_f32_16x16x32_bf16 v[46:49], v[138:141], v[162:165], v[46:49]
	ds_read_b128 v[150:153], v226 offset:2048
	v_mfma_f32_16x16x32_bf16 v[14:17], v[142:145], v[162:165], v[14:17]
	ds_read_b128 v[146:149], v226 offset:3072
	v_mfma_f32_16x16x32_bf16 v[106:109], v[130:133], v[166:169], v[106:109]
	ds_read_b128 v[174:177], v189
	v_mfma_f32_16x16x32_bf16 v[74:77], v[134:137], v[166:169], v[74:77]
	ds_read_b128 v[170:173], v189 offset:1024
	v_mfma_f32_16x16x32_bf16 v[42:45], v[138:141], v[166:169], v[42:45]
	ds_read_b128 v[162:165], v189 offset:3072
	v_mfma_f32_16x16x32_bf16 v[10:13], v[142:145], v[166:169], v[10:13]
	ds_read_b128 v[166:169], v189 offset:2048
	v_mfma_f32_16x16x32_bf16 v[102:105], v[130:133], v[234:237], v[102:105]
	v_mfma_f32_16x16x32_bf16 v[70:73], v[134:137], v[234:237], v[70:73]
	v_mfma_f32_16x16x32_bf16 v[38:41], v[138:141], v[234:237], v[38:41]
	v_mfma_f32_16x16x32_bf16 v[6:9], v[142:145], v[234:237], v[6:9]
	v_mfma_f32_16x16x32_bf16 v[94:97], v[130:133], v[238:241], v[94:97]
	v_mfma_f32_16x16x32_bf16 v[62:65], v[134:137], v[238:241], v[62:65]
	v_mfma_f32_16x16x32_bf16 v[30:33], v[138:141], v[238:241], v[30:33]
	v_mfma_f32_16x16x32_bf16 v[2:5], v[142:145], v[238:241], v[2:5]
	s_waitcnt lgkmcnt(0)
	v_mfma_f32_16x16x32_bf16 v[126:129], v[174:177], v[158:161], v[126:129]
	v_mfma_f32_16x16x32_bf16 v[98:101], v[170:173], v[158:161], v[98:101]
	v_add_u32_e32 v226, s35, v233
	ds_read_b128 v[234:237], v226
	v_mfma_f32_16x16x32_bf16 v[66:69], v[166:169], v[158:161], v[66:69]
	ds_read_b128 v[238:241], v226 offset:1024
	v_mfma_f32_16x16x32_bf16 v[34:37], v[162:165], v[158:161], v[34:37]
	ds_read_b128 v[182:185], v226 offset:2048
	v_mfma_f32_16x16x32_bf16 v[122:125], v[174:177], v[154:157], v[122:125]
	ds_read_b128 v[178:181], v226 offset:3072
	v_mfma_f32_16x16x32_bf16 v[90:93], v[170:173], v[154:157], v[90:93]
	v_mfma_f32_16x16x32_bf16 v[58:61], v[166:169], v[154:157], v[58:61]
	v_mfma_f32_16x16x32_bf16 v[26:29], v[162:165], v[154:157], v[26:29]
	v_mfma_f32_16x16x32_bf16 v[118:121], v[174:177], v[150:153], v[118:121]
	v_mfma_f32_16x16x32_bf16 v[86:89], v[170:173], v[150:153], v[86:89]
	v_mfma_f32_16x16x32_bf16 v[54:57], v[166:169], v[150:153], v[54:57]
	v_mfma_f32_16x16x32_bf16 v[22:25], v[162:165], v[150:153], v[22:25]
	v_mfma_f32_16x16x32_bf16 v[114:117], v[174:177], v[146:149], v[114:117]
	v_mfma_f32_16x16x32_bf16 v[82:85], v[170:173], v[146:149], v[82:85]
	v_mfma_f32_16x16x32_bf16 v[50:53], v[166:169], v[146:149], v[50:53]
	v_mfma_f32_16x16x32_bf16 v[18:21], v[162:165], v[146:149], v[18:21]
	s_waitcnt vmcnt(0)
	s_waitcnt lgkmcnt(0)
	s_barrier
	v_mfma_f32_16x16x32_bf16 v[110:113], v[174:177], v[234:237], v[110:113]
	s_add_i32 s24, s31, 0xffff8000
	s_and_b32 s24, s24, 0x10000
	v_add_u32_e32 v189, s24, v231
	v_add_u32_e32 v226, s24, v232
	ds_read_b128 v[158:161], v226
	v_mfma_f32_16x16x32_bf16 v[78:81], v[170:173], v[234:237], v[78:81]
	ds_read_b128 v[154:157], v226 offset:1024
	v_mfma_f32_16x16x32_bf16 v[46:49], v[166:169], v[234:237], v[46:49]
	ds_read_b128 v[150:153], v226 offset:2048
	v_mfma_f32_16x16x32_bf16 v[14:17], v[162:165], v[234:237], v[14:17]
	ds_read_b128 v[146:149], v226 offset:3072
	v_mfma_f32_16x16x32_bf16 v[106:109], v[174:177], v[238:241], v[106:109]
	ds_read_b128 v[130:133], v189
	v_mfma_f32_16x16x32_bf16 v[74:77], v[170:173], v[238:241], v[74:77]
	ds_read_b128 v[134:137], v189 offset:1024
	v_mfma_f32_16x16x32_bf16 v[42:45], v[166:169], v[238:241], v[42:45]
	ds_read_b128 v[138:141], v189 offset:2048
	v_mfma_f32_16x16x32_bf16 v[10:13], v[162:165], v[238:241], v[10:13]
	ds_read_b128 v[142:145], v189 offset:3072
	s_add_i32 s30, s30, 2
	s_add_u32 s20, s20, 0x80
	s_addc_u32 s21, s21, 0
	s_add_i32 s31, s31, 0x10000
	v_mfma_f32_16x16x32_bf16 v[102:105], v[174:177], v[182:185], v[102:105]
	v_mfma_f32_16x16x32_bf16 v[70:73], v[170:173], v[182:185], v[70:73]
	v_mfma_f32_16x16x32_bf16 v[38:41], v[166:169], v[182:185], v[38:41]
	v_mfma_f32_16x16x32_bf16 v[6:9], v[162:165], v[182:185], v[6:9]
	v_mfma_f32_16x16x32_bf16 v[94:97], v[174:177], v[178:181], v[94:97]
	v_mfma_f32_16x16x32_bf16 v[62:65], v[170:173], v[178:181], v[62:65]
	v_mfma_f32_16x16x32_bf16 v[30:33], v[166:169], v[178:181], v[30:33]
	v_mfma_f32_16x16x32_bf16 v[2:5], v[162:165], v[178:181], v[2:5]
	s_waitcnt lgkmcnt(0)
	v_mfma_f32_16x16x32_bf16 v[126:129], v[130:133], v[158:161], v[126:129]
	v_mfma_f32_16x16x32_bf16 v[98:101], v[134:137], v[158:161], v[98:101]
	s_add_i32 s28, s31, 0xfffe8000
	s_and_b32 s34, s28, 0x10000
	v_add_u32_e32 v170, s34, v233
	ds_read_b128 v[162:165], v170
	v_mfma_f32_16x16x32_bf16 v[66:69], v[138:141], v[158:161], v[66:69]
	ds_read_b128 v[166:169], v170 offset:1024
	v_mfma_f32_16x16x32_bf16 v[34:37], v[142:145], v[158:161], v[34:37]
	ds_read_b128 v[234:237], v170 offset:2048
	v_mfma_f32_16x16x32_bf16 v[122:125], v[130:133], v[154:157], v[122:125]
	ds_read_b128 v[238:241], v170 offset:3072
	v_mfma_f32_16x16x32_bf16 v[90:93], v[134:137], v[154:157], v[90:93]
	v_mfma_f32_16x16x32_bf16 v[58:61], v[138:141], v[154:157], v[58:61]
	v_mfma_f32_16x16x32_bf16 v[26:29], v[142:145], v[154:157], v[26:29]
	v_mfma_f32_16x16x32_bf16 v[118:121], v[130:133], v[150:153], v[118:121]
	v_mfma_f32_16x16x32_bf16 v[86:89], v[134:137], v[150:153], v[86:89]
	v_mfma_f32_16x16x32_bf16 v[54:57], v[138:141], v[150:153], v[54:57]
	v_mfma_f32_16x16x32_bf16 v[22:25], v[142:145], v[150:153], v[22:25]
	v_mfma_f32_16x16x32_bf16 v[114:117], v[130:133], v[146:149], v[114:117]
	v_mfma_f32_16x16x32_bf16 v[82:85], v[134:137], v[146:149], v[82:85]
	v_mfma_f32_16x16x32_bf16 v[50:53], v[138:141], v[146:149], v[50:53]
	v_mfma_f32_16x16x32_bf16 v[18:21], v[142:145], v[146:149], v[18:21]
	s_waitcnt vmcnt(0)
	s_waitcnt lgkmcnt(0)
	s_barrier
	v_mfma_f32_16x16x32_bf16 v[110:113], v[130:133], v[162:165], v[110:113]
	s_add_i32 s28, s31, 0xffff0000
	s_and_b32 s35, s28, 0x18000
	v_add_u32_e32 v189, s35, v231
	v_add_u32_e32 v226, s35, v232
	ds_read_b128 v[158:161], v226
	v_mfma_f32_16x16x32_bf16 v[78:81], v[134:137], v[162:165], v[78:81]
	ds_read_b128 v[154:157], v226 offset:1024
	v_mfma_f32_16x16x32_bf16 v[46:49], v[138:141], v[162:165], v[46:49]
	ds_read_b128 v[150:153], v226 offset:2048
	v_mfma_f32_16x16x32_bf16 v[14:17], v[142:145], v[162:165], v[14:17]
	ds_read_b128 v[146:149], v226 offset:3072
	v_mfma_f32_16x16x32_bf16 v[106:109], v[130:133], v[166:169], v[106:109]
	ds_read_b128 v[174:177], v189
	v_mfma_f32_16x16x32_bf16 v[74:77], v[134:137], v[166:169], v[74:77]
	ds_read_b128 v[170:173], v189 offset:1024
	v_mfma_f32_16x16x32_bf16 v[42:45], v[138:141], v[166:169], v[42:45]
	ds_read_b128 v[162:165], v189 offset:3072
	v_mfma_f32_16x16x32_bf16 v[10:13], v[142:145], v[166:169], v[10:13]
	ds_read_b128 v[166:169], v189 offset:2048
	v_mfma_f32_16x16x32_bf16 v[102:105], v[130:133], v[234:237], v[102:105]
	v_mfma_f32_16x16x32_bf16 v[70:73], v[134:137], v[234:237], v[70:73]
	v_mfma_f32_16x16x32_bf16 v[38:41], v[138:141], v[234:237], v[38:41]
	v_mfma_f32_16x16x32_bf16 v[6:9], v[142:145], v[234:237], v[6:9]
	v_mfma_f32_16x16x32_bf16 v[94:97], v[130:133], v[238:241], v[94:97]
	v_mfma_f32_16x16x32_bf16 v[62:65], v[134:137], v[238:241], v[62:65]
	v_mfma_f32_16x16x32_bf16 v[30:33], v[138:141], v[238:241], v[30:33]
	v_mfma_f32_16x16x32_bf16 v[2:5], v[142:145], v[238:241], v[2:5]
	s_waitcnt lgkmcnt(0)
	v_mfma_f32_16x16x32_bf16 v[126:129], v[174:177], v[158:161], v[126:129]
	v_mfma_f32_16x16x32_bf16 v[98:101], v[170:173], v[158:161], v[98:101]
	v_add_u32_e32 v226, s35, v233
	ds_read_b128 v[234:237], v226
	v_mfma_f32_16x16x32_bf16 v[66:69], v[166:169], v[158:161], v[66:69]
	ds_read_b128 v[238:241], v226 offset:1024
	v_mfma_f32_16x16x32_bf16 v[34:37], v[162:165], v[158:161], v[34:37]
	ds_read_b128 v[182:185], v226 offset:2048
	v_mfma_f32_16x16x32_bf16 v[122:125], v[174:177], v[154:157], v[122:125]
	ds_read_b128 v[178:181], v226 offset:3072
	v_mfma_f32_16x16x32_bf16 v[90:93], v[170:173], v[154:157], v[90:93]
	v_mfma_f32_16x16x32_bf16 v[58:61], v[166:169], v[154:157], v[58:61]
	v_mfma_f32_16x16x32_bf16 v[26:29], v[162:165], v[154:157], v[26:29]
	v_mfma_f32_16x16x32_bf16 v[118:121], v[174:177], v[150:153], v[118:121]
	v_mfma_f32_16x16x32_bf16 v[86:89], v[170:173], v[150:153], v[86:89]
	v_mfma_f32_16x16x32_bf16 v[54:57], v[166:169], v[150:153], v[54:57]
	v_mfma_f32_16x16x32_bf16 v[22:25], v[162:165], v[150:153], v[22:25]
	v_mfma_f32_16x16x32_bf16 v[114:117], v[174:177], v[146:149], v[114:117]
	v_mfma_f32_16x16x32_bf16 v[82:85], v[170:173], v[146:149], v[82:85]
	v_mfma_f32_16x16x32_bf16 v[50:53], v[166:169], v[146:149], v[50:53]
	v_mfma_f32_16x16x32_bf16 v[18:21], v[162:165], v[146:149], v[18:21]
	s_waitcnt vmcnt(0)
	s_waitcnt lgkmcnt(0)
	s_barrier
	v_mfma_f32_16x16x32_bf16 v[110:113], v[174:177], v[234:237], v[110:113]
	v_mfma_f32_16x16x32_bf16 v[78:81], v[170:173], v[234:237], v[78:81]
	v_mfma_f32_16x16x32_bf16 v[46:49], v[166:169], v[234:237], v[46:49]
	v_mfma_f32_16x16x32_bf16 v[14:17], v[162:165], v[234:237], v[14:17]
	v_mfma_f32_16x16x32_bf16 v[106:109], v[174:177], v[238:241], v[106:109]
	v_mfma_f32_16x16x32_bf16 v[74:77], v[170:173], v[238:241], v[74:77]
	v_mfma_f32_16x16x32_bf16 v[42:45], v[166:169], v[238:241], v[42:45]
	v_mfma_f32_16x16x32_bf16 v[10:13], v[162:165], v[238:241], v[10:13]
	s_add_i32 s30, s30, 2
	s_add_u32 s20, s20, 0x80
	s_addc_u32 s21, s21, 0
	s_add_i32 s31, s31, 0x10000
	v_mfma_f32_16x16x32_bf16 v[102:105], v[174:177], v[182:185], v[102:105]
	v_mfma_f32_16x16x32_bf16 v[70:73], v[170:173], v[182:185], v[70:73]
	v_mfma_f32_16x16x32_bf16 v[38:41], v[166:169], v[182:185], v[38:41]
	v_mfma_f32_16x16x32_bf16 v[6:9], v[162:165], v[182:185], v[6:9]
	v_mfma_f32_16x16x32_bf16 v[94:97], v[174:177], v[178:181], v[94:97]
	v_mfma_f32_16x16x32_bf16 v[62:65], v[170:173], v[178:181], v[62:65]
	v_mfma_f32_16x16x32_bf16 v[30:33], v[166:169], v[178:181], v[30:33]
	v_mfma_f32_16x16x32_bf16 v[2:5], v[162:165], v[178:181], v[2:5]
	s_branch .LBB0_659
